# static s_setprio 1 for waves 4-7 (the half running one phase behind) inside every GEMM k-loop, on top of v35
# speedup vs baseline: 1.0151x; 1.0020x over previous
; __device__ __forceinline__ int otid() { int t = threadIdx.x; asm volatile("" : "+v"(t)); return t; }
; #define GEMM_WAITV(n) asm volatile("s_waitcnt vmcnt(" #n ")" ::: "memory")
; template <bool SWAP>
; __device__ __forceinline__ void gemm_main(f32x4 (&acc)[8][4], const TP& t, int nk, char* lds) {
;   const u16* a0 = t.a0; const u16* a1 = t.a1; const u16* b0 = t.b0; const u16* b1 = t.b1;
;   const int tid = otid(), lane = tid & 63, wave = tid >> 6;
;   const int wm = wave >> 2, wn = wave & 3, lr = lane & 15, lq = lane >> 4;
;   const int ldoff = wave * 2048 + lane * 16;
;   const int sw = (lq ^ ((0 - (lr >> 2)) & 3)) << 4;
;   const int aoff = (wm * 128 + lr) * 64 + sw, boff = T_ASTAGE + (wn * 64 + lr) * 64 + sw;
;     ...
; #pragma unroll 1
;   for (int kt = 0; kt < nk - 3; ++kt) {
;     GEMM_WAITV(8);
;     GEMM_STEP(kt, true)
; __device__ __forceinline__ void zero_acc(f32x4 (&acc)[8][4]) {
; #pragma unroll
;   for (int i = 0; i < 8; ++i)
; #pragma unroll
;     for (int j = 0; j < 4; ++j) acc[i][j] = (f32x4){0.f, 0.f, 0.f, 0.f};
; }
.LBB0_385:
	s_mov_b64 s[34:35], -1
	s_andn2_b64 vcc, exec, s[36:37]
	v_lshl_add_u64 v[128:129], v[158:159], 0, s[20:21]
	v_lshl_add_u64 v[130:131], v[156:157], 0, s[20:21]
	v_lshl_add_u64 v[132:133], v[146:147], 0, s[20:21]
	v_lshl_add_u64 v[134:135], v[160:161], 0, s[20:21]
	s_cbranch_vccz .LBB0_401
	v_mov_b32_e32 v0, v153
	v_lshl_add_u64 v[136:137], v[158:159], 0, s[20:21]
	v_lshlrev_b32_e32 v3, 2, v0
	v_and_b32_e32 v3, 48, v3
	v_sub_u32_e32 v3, 0, v3
	v_and_b32_e32 v164, 15, v0
	v_lshlrev_b32_e32 v1, 5, v0
	v_lshlrev_b32_e32 v2, 4, v0
	v_bitop3_b32 v165, v0, 48, v3 bitop3:0x48
	v_ashrrev_i32_e32 v166, 1, v0
	v_lshlrev_b32_e32 v0, 6, v0
	v_and_b32_e32 v1, 0xfffff800, v1
	v_and_b32_e32 v2, 0x3f0, v2
	v_and_or_b32 v3, v166, s41, v164
	v_and_b32_e32 v167, 0x33c0, v0
	v_mov_b32_e32 v0, 0
	v_lshl_or_b32 v168, v3, 6, v165
	v_or_b32_e32 v170, v167, v165
	v_add3_u32 v171, 0, v1, v2
	v_lshl_add_u64 v[138:139], v[156:157], 0, s[20:21]
	v_lshl_add_u64 v[140:141], v[146:147], 0, s[20:21]
	v_lshl_add_u64 v[142:143], v[160:161], 0, s[20:21]
	s_mov_b32 s34, 0x18000
	v_mov_b32_e32 v1, v0
	v_mov_b32_e32 v2, v0
	v_mov_b32_e32 v3, v0
	v_mov_b32_e32 v4, v0
	v_mov_b32_e32 v5, v0
	v_mov_b32_e32 v6, v0
	v_mov_b32_e32 v7, v0
	v_mov_b32_e32 v8, v0
	v_mov_b32_e32 v9, v0
	v_mov_b32_e32 v10, v0
	v_mov_b32_e32 v11, v0
	v_mov_b32_e32 v12, v0
	v_mov_b32_e32 v13, v0
	v_mov_b32_e32 v14, v0
	v_mov_b32_e32 v15, v0
	v_mov_b32_e32 v16, v0
	v_mov_b32_e32 v17, v0
	v_mov_b32_e32 v18, v0
	v_mov_b32_e32 v19, v0
	v_mov_b32_e32 v20, v0
	v_mov_b32_e32 v21, v0
	v_mov_b32_e32 v22, v0
	v_mov_b32_e32 v23, v0
	v_mov_b32_e32 v24, v0
	v_mov_b32_e32 v25, v0
	v_mov_b32_e32 v26, v0
	v_mov_b32_e32 v27, v0
	v_mov_b32_e32 v28, v0
	v_mov_b32_e32 v29, v0
	v_mov_b32_e32 v30, v0
	v_mov_b32_e32 v31, v0
	v_mov_b32_e32 v32, v0
	v_mov_b32_e32 v33, v0
	v_mov_b32_e32 v34, v0
	v_mov_b32_e32 v35, v0
	v_mov_b32_e32 v36, v0
	v_mov_b32_e32 v37, v0
	v_mov_b32_e32 v38, v0
	v_mov_b32_e32 v39, v0
	v_mov_b32_e32 v40, v0
	v_mov_b32_e32 v41, v0
	v_mov_b32_e32 v42, v0
	v_mov_b32_e32 v43, v0
	v_mov_b32_e32 v44, v0
	v_mov_b32_e32 v45, v0
	v_mov_b32_e32 v46, v0
	v_mov_b32_e32 v47, v0
	v_mov_b32_e32 v48, v0
	v_mov_b32_e32 v49, v0
	v_mov_b32_e32 v50, v0
	v_mov_b32_e32 v51, v0
	v_mov_b32_e32 v52, v0
	v_mov_b32_e32 v53, v0
	v_mov_b32_e32 v54, v0
	v_mov_b32_e32 v55, v0
	v_mov_b32_e32 v56, v0
	v_mov_b32_e32 v57, v0
	v_mov_b32_e32 v58, v0
	v_mov_b32_e32 v59, v0
	v_mov_b32_e32 v60, v0
	v_mov_b32_e32 v61, v0
	v_mov_b32_e32 v62, v0
	v_mov_b32_e32 v63, v0
	v_mov_b32_e32 v64, v0
	v_mov_b32_e32 v65, v0
	v_mov_b32_e32 v66, v0
	v_mov_b32_e32 v67, v0
	v_mov_b32_e32 v68, v0
	v_mov_b32_e32 v69, v0
	v_mov_b32_e32 v70, v0
	v_mov_b32_e32 v71, v0
	v_mov_b32_e32 v72, v0
	v_mov_b32_e32 v73, v0
	v_mov_b32_e32 v74, v0
	v_mov_b32_e32 v75, v0
	v_mov_b32_e32 v76, v0
	v_mov_b32_e32 v77, v0
	v_mov_b32_e32 v78, v0
	v_mov_b32_e32 v79, v0
	v_mov_b32_e32 v80, v0
	v_mov_b32_e32 v81, v0
	v_mov_b32_e32 v82, v0
	v_mov_b32_e32 v83, v0
	v_mov_b32_e32 v84, v0
	v_mov_b32_e32 v85, v0
	v_mov_b32_e32 v86, v0
	v_mov_b32_e32 v87, v0
	v_mov_b32_e32 v88, v0
	v_mov_b32_e32 v89, v0
	v_mov_b32_e32 v90, v0
	v_mov_b32_e32 v91, v0
	v_mov_b32_e32 v92, v0
	v_mov_b32_e32 v93, v0
	v_mov_b32_e32 v94, v0
	v_mov_b32_e32 v95, v0
	v_mov_b32_e32 v96, v0
	v_mov_b32_e32 v97, v0
	v_mov_b32_e32 v98, v0
	v_mov_b32_e32 v99, v0
	v_mov_b32_e32 v100, v0
	v_mov_b32_e32 v101, v0
	v_mov_b32_e32 v102, v0
	v_mov_b32_e32 v103, v0
	v_mov_b32_e32 v104, v0
	v_mov_b32_e32 v105, v0
	v_mov_b32_e32 v106, v0
	v_mov_b32_e32 v107, v0
	v_mov_b32_e32 v108, v0
	v_mov_b32_e32 v109, v0
	v_mov_b32_e32 v110, v0
	v_mov_b32_e32 v111, v0
	v_mov_b32_e32 v112, v0
	v_mov_b32_e32 v113, v0
	v_mov_b32_e32 v114, v0
	v_mov_b32_e32 v115, v0
	v_mov_b32_e32 v116, v0
	v_mov_b32_e32 v117, v0
	v_mov_b32_e32 v118, v0
	v_mov_b32_e32 v119, v0
	v_mov_b32_e32 v120, v0
	v_mov_b32_e32 v121, v0
	v_mov_b32_e32 v122, v0
	v_mov_b32_e32 v123, v0
	v_mov_b32_e32 v124, v0
	v_mov_b32_e32 v125, v0
	v_mov_b32_e32 v126, v0
	v_mov_b32_e32 v127, v0
	v_readfirstlane_b32 s98, v171
	s_waitcnt vmcnt(8)
	s_barrier
	s_cmp_lt_u32 s98, 0x2000
	s_cbranch_scc1 .Lp2a_top
	s_barrier
	s_setprio 1

; template <bool SWAP>
; __device__ __forceinline__ void gemm_main(f32x4 (&acc)[8][4], const TP& t, int nk, char* lds) {
;     ...
;   __builtin_amdgcn_s_barrier();
; }
.Lp2a_done:
	s_setprio 0
	s_nop 7

; __device__ __forceinline__ int otid() { int t = threadIdx.x; asm volatile("" : "+v"(t)); return t; }
; #define GEMM_WAITV(n) asm volatile("s_waitcnt vmcnt(" #n ")" ::: "memory")
; template <bool SWAP>
; __device__ __forceinline__ void gemm_main(f32x4 (&acc)[8][4], const TP& t, int nk, char* lds) {
;   const u16* a0 = t.a0; const u16* a1 = t.a1; const u16* b0 = t.b0; const u16* b1 = t.b1;
;   const int tid = otid(), lane = tid & 63, wave = tid >> 6;
;   const int wm = wave >> 2, wn = wave & 3, lr = lane & 15, lq = lane >> 4;
;   const int ldoff = wave * 2048 + lane * 16;
;   const int sw = (lq ^ ((0 - (lr >> 2)) & 3)) << 4;
;   const int aoff = (wm * 128 + lr) * 64 + sw, boff = T_ASTAGE + (wn * 64 + lr) * 64 + sw;
;     ...
; #pragma unroll 1
;   for (int kt = 0; kt < nk - 3; ++kt) {
;     GEMM_WAITV(8);
;     GEMM_STEP(kt, true)
; __device__ __forceinline__ void zero_acc(f32x4 (&acc)[8][4]) {
; #pragma unroll
;   for (int i = 0; i < 8; ++i)
; #pragma unroll
;     for (int j = 0; j < 4; ++j) acc[i][j] = (f32x4){0.f, 0.f, 0.f, 0.f};
; }
.LBB0_401:
	s_and_b64 vcc, exec, s[34:35]
	s_cbranch_vccz .LBB0_417
	s_nop 2
	v_mov_b32_e32 v0, v153
	s_mov_b32 s34, 0x18000
	v_lshlrev_b32_e32 v3, 2, v0
	v_and_b32_e32 v3, 48, v3
	v_sub_u32_e32 v3, 0, v3
	v_and_b32_e32 v136, 15, v0
	v_lshlrev_b32_e32 v1, 5, v0
	v_lshlrev_b32_e32 v2, 4, v0
	v_bitop3_b32 v137, v0, 48, v3 bitop3:0x48
	v_ashrrev_i32_e32 v138, 1, v0
	v_lshlrev_b32_e32 v0, 6, v0
	v_and_b32_e32 v1, 0xfffff800, v1
	v_and_b32_e32 v2, 0x3f0, v2
	v_and_or_b32 v3, v138, s41, v136
	v_and_b32_e32 v139, 0x33c0, v0
	v_mov_b32_e32 v0, 0
	v_lshl_or_b32 v140, v3, 6, v137
	v_or_b32_e32 v141, v139, v137
	v_add3_u32 v142, 0, v1, v2
	v_mov_b32_e32 v1, v0
	v_mov_b32_e32 v2, v0
	v_mov_b32_e32 v3, v0
	v_mov_b32_e32 v4, v0
	v_mov_b32_e32 v5, v0
	v_mov_b32_e32 v6, v0
	v_mov_b32_e32 v7, v0
	v_mov_b32_e32 v8, v0
	v_mov_b32_e32 v9, v0
	v_mov_b32_e32 v10, v0
	v_mov_b32_e32 v11, v0
	v_mov_b32_e32 v12, v0
	v_mov_b32_e32 v13, v0
	v_mov_b32_e32 v14, v0
	v_mov_b32_e32 v15, v0
	v_mov_b32_e32 v16, v0
	v_mov_b32_e32 v17, v0
	v_mov_b32_e32 v18, v0
	v_mov_b32_e32 v19, v0
	v_mov_b32_e32 v20, v0
	v_mov_b32_e32 v21, v0
	v_mov_b32_e32 v22, v0
	v_mov_b32_e32 v23, v0
	v_mov_b32_e32 v24, v0
	v_mov_b32_e32 v25, v0
	v_mov_b32_e32 v26, v0
	v_mov_b32_e32 v27, v0
	v_mov_b32_e32 v28, v0
	v_mov_b32_e32 v29, v0
	v_mov_b32_e32 v30, v0
	v_mov_b32_e32 v31, v0
	v_mov_b32_e32 v32, v0
	v_mov_b32_e32 v33, v0
	v_mov_b32_e32 v34, v0
	v_mov_b32_e32 v35, v0
	v_mov_b32_e32 v36, v0
	v_mov_b32_e32 v37, v0
	v_mov_b32_e32 v38, v0
	v_mov_b32_e32 v39, v0
	v_mov_b32_e32 v40, v0
	v_mov_b32_e32 v41, v0
	v_mov_b32_e32 v42, v0
	v_mov_b32_e32 v43, v0
	v_mov_b32_e32 v44, v0
	v_mov_b32_e32 v45, v0
	v_mov_b32_e32 v46, v0
	v_mov_b32_e32 v47, v0
	v_mov_b32_e32 v48, v0
	v_mov_b32_e32 v49, v0
	v_mov_b32_e32 v50, v0
	v_mov_b32_e32 v51, v0
	v_mov_b32_e32 v52, v0
	v_mov_b32_e32 v53, v0
	v_mov_b32_e32 v54, v0
	v_mov_b32_e32 v55, v0
	v_mov_b32_e32 v56, v0
	v_mov_b32_e32 v57, v0
	v_mov_b32_e32 v58, v0
	v_mov_b32_e32 v59, v0
	v_mov_b32_e32 v60, v0
	v_mov_b32_e32 v61, v0
	v_mov_b32_e32 v62, v0
	v_mov_b32_e32 v63, v0
	v_mov_b32_e32 v64, v0
	v_mov_b32_e32 v65, v0
	v_mov_b32_e32 v66, v0
	v_mov_b32_e32 v67, v0
	v_mov_b32_e32 v68, v0
	v_mov_b32_e32 v69, v0
	v_mov_b32_e32 v70, v0
	v_mov_b32_e32 v71, v0
	v_mov_b32_e32 v72, v0
	v_mov_b32_e32 v73, v0
	v_mov_b32_e32 v74, v0
	v_mov_b32_e32 v75, v0
	v_mov_b32_e32 v76, v0
	v_mov_b32_e32 v77, v0
	v_mov_b32_e32 v78, v0
	v_mov_b32_e32 v79, v0
	v_mov_b32_e32 v80, v0
	v_mov_b32_e32 v81, v0
	v_mov_b32_e32 v82, v0
	v_mov_b32_e32 v83, v0
	v_mov_b32_e32 v84, v0
	v_mov_b32_e32 v85, v0
	v_mov_b32_e32 v86, v0
	v_mov_b32_e32 v87, v0
	v_mov_b32_e32 v88, v0
	v_mov_b32_e32 v89, v0
	v_mov_b32_e32 v90, v0
	v_mov_b32_e32 v91, v0
	v_mov_b32_e32 v92, v0
	v_mov_b32_e32 v93, v0
	v_mov_b32_e32 v94, v0
	v_mov_b32_e32 v95, v0
	v_mov_b32_e32 v96, v0
	v_mov_b32_e32 v97, v0
	v_mov_b32_e32 v98, v0
	v_mov_b32_e32 v99, v0
	v_mov_b32_e32 v100, v0
	v_mov_b32_e32 v101, v0
	v_mov_b32_e32 v102, v0
	v_mov_b32_e32 v103, v0
	v_mov_b32_e32 v104, v0
	v_mov_b32_e32 v105, v0
	v_mov_b32_e32 v106, v0
	v_mov_b32_e32 v107, v0
	v_mov_b32_e32 v108, v0
	v_mov_b32_e32 v109, v0
	v_mov_b32_e32 v110, v0
	v_mov_b32_e32 v111, v0
	v_mov_b32_e32 v112, v0
	v_mov_b32_e32 v113, v0
	v_mov_b32_e32 v114, v0
	v_mov_b32_e32 v115, v0
	v_mov_b32_e32 v116, v0
	v_mov_b32_e32 v117, v0
	v_mov_b32_e32 v118, v0
	v_mov_b32_e32 v119, v0
	v_mov_b32_e32 v120, v0
	v_mov_b32_e32 v121, v0
	v_mov_b32_e32 v122, v0
	v_mov_b32_e32 v123, v0
	v_mov_b32_e32 v124, v0
	v_mov_b32_e32 v125, v0
	v_mov_b32_e32 v126, v0
	v_mov_b32_e32 v127, v0
	v_readfirstlane_b32 s98, v142
	s_waitcnt vmcnt(8)
	s_barrier
	s_cmp_lt_u32 s98, 0x2000
	s_cbranch_scc1 .Lp2b_top
	s_barrier
	s_setprio 1

; __device__ __forceinline__ void zero_acc(f32x4 (&acc)[8][4]) {
; #pragma unroll
;   for (int i = 0; i < 8; ++i)
; #pragma unroll
;     for (int j = 0; j < 4; ++j) acc[i][j] = (f32x4){0.f, 0.f, 0.f, 0.f};
; }
; __device__ __forceinline__ void merge_phase(const Params& p, int first, int step, int n, char* lds) {
;     ...
;   TP cur = merge_ptrs(p, first >> 2, first & 3, 0);
;   gemm_issue3(cur, lds);
; #pragma unroll 1
;   for (int it = first; it < n; it += step) {
;     const int mt = it >> 2, nt = it & 3;
;     f32x4 acc[8][4];
;     zero_acc(acc);
;     gemm_main<true>(acc, cur, 16, lds);
.LBB0_845:
	v_mov_b32_e32 v0, v153
	v_mov_b32_e32 v8, 0
	v_lshlrev_b32_e32 v3, 2, v0
	v_and_b32_e32 v3, 48, v3
	v_sub_u32_e32 v3, 0, v3
	v_and_b32_e32 v136, 15, v0
	v_lshlrev_b32_e32 v1, 5, v0
	v_lshlrev_b32_e32 v2, 4, v0
	v_bitop3_b32 v137, v0, 48, v3 bitop3:0x48
	v_ashrrev_i32_e32 v138, 1, v0
	v_lshlrev_b32_e32 v0, 6, v0
	v_and_b32_e32 v1, 0xfffff800, v1
	v_and_b32_e32 v2, 0x3f0, v2
	v_and_or_b32 v3, v138, s68, v136
	v_and_b32_e32 v139, 0x33c0, v0
	v_lshl_or_b32 v140, v3, 6, v137
	v_or_b32_e32 v141, v139, v137
	v_add3_u32 v142, 0, v1, v2
	v_lshl_add_u64 v[128:129], v[158:159], 0, s[40:41]
	v_lshl_add_u64 v[130:131], v[162:163], 0, s[40:41]
	v_lshl_add_u64 v[132:133], v[160:161], 0, s[40:41]
	v_lshl_add_u64 v[134:135], v[164:165], 0, s[40:41]
	s_mov_b32 s46, 0x18000
	v_mov_b32_e32 v9, v8
	v_mov_b32_e32 v10, v8
	v_mov_b32_e32 v11, v8
	v_mov_b32_e32 v24, v8
	v_mov_b32_e32 v25, v8
	v_mov_b32_e32 v26, v8
	v_mov_b32_e32 v27, v8
	v_mov_b32_e32 v32, v8
	v_mov_b32_e32 v33, v8
	v_mov_b32_e32 v34, v8
	v_mov_b32_e32 v35, v8
	v_mov_b32_e32 v36, v8
	v_mov_b32_e32 v37, v8
	v_mov_b32_e32 v38, v8
	v_mov_b32_e32 v39, v8
	v_mov_b32_e32 v44, v8
	v_mov_b32_e32 v45, v8
	v_mov_b32_e32 v46, v8
	v_mov_b32_e32 v47, v8
	v_mov_b32_e32 v60, v8
	v_mov_b32_e32 v61, v8
	v_mov_b32_e32 v62, v8
	v_mov_b32_e32 v63, v8
	v_mov_b32_e32 v64, v8
	v_mov_b32_e32 v65, v8
	v_mov_b32_e32 v66, v8
	v_mov_b32_e32 v67, v8
	v_mov_b32_e32 v84, v8
	v_mov_b32_e32 v85, v8
	v_mov_b32_e32 v86, v8
	v_mov_b32_e32 v87, v8
	v_mov_b32_e32 v88, v8
	v_mov_b32_e32 v89, v8
	v_mov_b32_e32 v90, v8
	v_mov_b32_e32 v91, v8
	v_mov_b32_e32 v92, v8
	v_mov_b32_e32 v93, v8
	v_mov_b32_e32 v94, v8
	v_mov_b32_e32 v95, v8
	v_mov_b32_e32 v112, v8
	v_mov_b32_e32 v113, v8
	v_mov_b32_e32 v114, v8
	v_mov_b32_e32 v115, v8
	v_mov_b32_e32 v124, v8
	v_mov_b32_e32 v125, v8
	v_mov_b32_e32 v126, v8
	v_mov_b32_e32 v127, v8
	v_mov_b32_e32 v116, v8
	v_mov_b32_e32 v117, v8
	v_mov_b32_e32 v118, v8
	v_mov_b32_e32 v119, v8
	v_mov_b32_e32 v120, v8
	v_mov_b32_e32 v121, v8
	v_mov_b32_e32 v122, v8
	v_mov_b32_e32 v123, v8
	v_mov_b32_e32 v108, v8
	v_mov_b32_e32 v109, v8
	v_mov_b32_e32 v110, v8
	v_mov_b32_e32 v111, v8
	v_mov_b32_e32 v104, v8
	v_mov_b32_e32 v105, v8
	v_mov_b32_e32 v106, v8
	v_mov_b32_e32 v107, v8
	v_mov_b32_e32 v96, v8
	v_mov_b32_e32 v97, v8
	v_mov_b32_e32 v98, v8
	v_mov_b32_e32 v99, v8
	v_mov_b32_e32 v100, v8
	v_mov_b32_e32 v101, v8
	v_mov_b32_e32 v102, v8
	v_mov_b32_e32 v103, v8
	v_mov_b32_e32 v80, v8
	v_mov_b32_e32 v81, v8
	v_mov_b32_e32 v82, v8
	v_mov_b32_e32 v83, v8
	v_mov_b32_e32 v76, v8
	v_mov_b32_e32 v77, v8
	v_mov_b32_e32 v78, v8
	v_mov_b32_e32 v79, v8
	v_mov_b32_e32 v68, v8
	v_mov_b32_e32 v69, v8
	v_mov_b32_e32 v70, v8
	v_mov_b32_e32 v71, v8
	v_mov_b32_e32 v72, v8
	v_mov_b32_e32 v73, v8
	v_mov_b32_e32 v74, v8
	v_mov_b32_e32 v75, v8
	v_mov_b32_e32 v56, v8
	v_mov_b32_e32 v57, v8
	v_mov_b32_e32 v58, v8
	v_mov_b32_e32 v59, v8
	v_mov_b32_e32 v52, v8
	v_mov_b32_e32 v53, v8
	v_mov_b32_e32 v54, v8
	v_mov_b32_e32 v55, v8
	v_mov_b32_e32 v40, v8
	v_mov_b32_e32 v41, v8
	v_mov_b32_e32 v42, v8
	v_mov_b32_e32 v43, v8
	v_mov_b32_e32 v48, v8
	v_mov_b32_e32 v49, v8
	v_mov_b32_e32 v50, v8
	v_mov_b32_e32 v51, v8
	v_mov_b32_e32 v28, v8
	v_mov_b32_e32 v29, v8
	v_mov_b32_e32 v30, v8
	v_mov_b32_e32 v31, v8
	v_mov_b32_e32 v20, v8
	v_mov_b32_e32 v21, v8
	v_mov_b32_e32 v22, v8
	v_mov_b32_e32 v23, v8
	v_mov_b32_e32 v12, v8
	v_mov_b32_e32 v13, v8
	v_mov_b32_e32 v14, v8
	v_mov_b32_e32 v15, v8
	v_mov_b32_e32 v16, v8
	v_mov_b32_e32 v17, v8
	v_mov_b32_e32 v18, v8
	v_mov_b32_e32 v19, v8
	v_mov_b32_e32 v4, v8
	v_mov_b32_e32 v5, v8
	v_mov_b32_e32 v6, v8
	v_mov_b32_e32 v7, v8
	v_mov_b32_e32 v0, v8
	v_mov_b32_e32 v1, v8
	v_mov_b32_e32 v2, v8
	v_mov_b32_e32 v3, v8
	v_readfirstlane_b32 s98, v142
	s_waitcnt vmcnt(8)
	s_barrier
	s_cmp_lt_u32 s98, 0x2000
	s_cbranch_scc1 .Lmg1_top
	s_barrier
	s_setprio 1

; __device__ __forceinline__ int trow(int j) { const int t = otid(); return ((t >> 6) * 2 + j) * 16 + ((t & 63) >> 2); }
; __device__ __forceinline__ int tkc() { const int l = otid() & 63; return ((l & 3) ^ ((0 - (l >> 4)) & 3)) * 8; }
; __device__ __forceinline__ int perm_row(int R) { return (R & ~63) | (((R >> 2) & 3) * 16 + ((R >> 4) & 3) * 4 + (R & 3)); }
; __device__ __forceinline__ TP merge_ptrs(const Params& p, int mt, int nt, int br) {
;   TP t;
;   t.a0 = (const u16*)(p.ws + (br ? OFF_NA : OFF_HY)) + (size_t)(mt * 256 + trow(0)) * 512 + tkc(); t.a1 = t.a0 + 16 * 512;
;   t.b0 = (const u16*)(p.ws + (br ? OFF_WBN : OFF_WBH)) + (size_t)(nt * 256 + perm_row(trow(0))) * 512 + tkc();
;   t.b1 = (const u16*)(p.ws + (br ? OFF_WBN : OFF_WBH)) + (size_t)(nt * 256 + perm_row(trow(1))) * 512 + tkc();
;   return t;
; }
; __device__ __forceinline__ void merge_phase(const Params& p, int first, int step, int n, char* lds) {
;     ...
;     cur = merge_ptrs(p, mt, nt, 1);
;     gemm_issue3(cur, lds);
; #pragma unroll
;     for (int i = 0; i < 8; ++i) {
;       const int m = mt * 256 + wm * 128 + i * 16 + lr;
;       const int n0 = nt * 256 + wn * 64 + lq * 16;
;       union { uint4 v[2]; u16 e[16]; } gh, gn;
;       gh.v[0] = *(const uint4*)(gates + (size_t)m * 2048 + n0); gh.v[1] = *(const uint4*)(gates + (size_t)m * 2048 + n0 + 8);
;       gn.v[0] = *(const uint4*)(gates + (size_t)m * 2048 + 1024 + n0); gn.v[1] = *(const uint4*)(gates + (size_t)m * 2048 + 1024 + n0 + 8);
.LBB0_859:
	s_lshl_b32 s54, s71, 6
	v_mov_b32_e32 v128, v153
	s_barrier
	s_and_b32 s54, s54, 0xffffff00
	v_mov_b32_e32 v199, v153
	v_ashrrev_i32_e32 v129, 1, v128
	v_bfe_u32 v198, v128, 2, 4
	v_and_b32_e32 v155, 0xffffffe0, v129
	v_or_b32_e32 v128, s54, v198
	v_add_u32_e32 v128, v128, v155
	v_lshrrev_b32_e32 v130, 4, v199
	v_sub_u32_e32 v200, 0, v130
	v_ashrrev_i32_e32 v129, 31, v128
	v_xor_b32_e32 v130, v199, v200
	v_lshlrev_b64 v[128:129], 10, v[128:129]
	v_lshlrev_b32_e32 v130, 4, v130
	v_lshl_add_u64 v[128:129], s[22:23], 0, v[128:129]
	v_and_b32_e32 v156, 48, v130
	v_lshl_add_u64 v[158:159], v[128:129], 0, v[156:157]
	v_mov_b32_e32 v128, v153
	s_lshl_b32 s55, s71, 8
	s_and_b32 s55, s55, 0x300
	v_ashrrev_i32_e32 v129, 1, v128
	v_and_b32_e32 v201, 0xffffffc0, v129
	v_and_b32_e32 v202, 48, v128
	v_lshrrev_b32_e32 v129, 2, v129
	v_bfe_u32 v204, v128, 2, 2
	v_mov_b32_e32 v205, v153
	v_and_b32_e32 v203, 8, v129
	v_or_b32_e32 v128, v202, v204
	v_add_u32_e32 v129, s55, v201
	v_or3_b32 v128, v129, v128, v203
	v_lshrrev_b32_e32 v130, 4, v205
	v_sub_u32_e32 v206, 0, v130
	v_ashrrev_i32_e32 v129, 31, v128
	v_xor_b32_e32 v130, v205, v206
	v_lshlrev_b64 v[128:129], 10, v[128:129]
	v_lshlrev_b32_e32 v130, 4, v130
	v_lshl_add_u64 v[128:129], s[24:25], 0, v[128:129]
	v_and_b32_e32 v156, 48, v130
	v_lshl_add_u64 v[160:161], v[128:129], 0, v[156:157]
	v_mov_b32_e32 v128, v153
	v_mov_b32_e32 v211, v153
	v_ashrrev_i32_e32 v129, 1, v128
	v_and_b32_e32 v208, 48, v128
	v_bfe_u32 v210, v128, 2, 2
	v_and_b32_e32 v207, 0xffffffc0, v129
	v_lshrrev_b32_e32 v129, 2, v129
	v_or3_b32 v128, v208, v210, s55
	v_and_b32_e32 v209, 8, v129
	v_add_u32_e32 v128, v207, v128
	v_or3_b32 v128, v128, v209, 4
	v_lshrrev_b32_e32 v130, 4, v211
	v_sub_u32_e32 v212, 0, v130
	v_ashrrev_i32_e32 v129, 31, v128
	v_xor_b32_e32 v130, v211, v212
	v_lshlrev_b64 v[128:129], 10, v[128:129]
	v_lshlrev_b32_e32 v130, 4, v130
	v_add_u32_e32 v166, s54, v149
	v_lshl_add_u64 v[128:129], s[24:25], 0, v[128:129]
	v_and_b32_e32 v156, 48, v130
	v_ashrrev_i32_e32 v167, 31, v166
	v_lshl_add_u64 v[164:165], v[128:129], 0, v[156:157]
	v_or_b32_e32 v168, s55, v151
	v_lshlrev_b64 v[128:129], 12, v[166:167]
	v_lshl_add_u64 v[128:129], s[12:13], 0, v[128:129]
	v_lshlrev_b32_e32 v156, 1, v168
	v_mov_b32_e32 v130, v153
	v_lshl_add_u64 v[170:171], v[128:129], 0, v[156:157]
	global_load_dwordx4 v[136:139], v[170:171], off offset:2048
	global_load_dwordx4 v[132:135], v[170:171], off offset:2064
	global_load_dwordx4 v[144:147], v[170:171], off
	global_load_dwordx4 v[140:143], v[170:171], off offset:16
	v_lshlrev_b32_e32 v128, 5, v130
	v_lshlrev_b32_e32 v129, 4, v130
	v_and_b32_e32 v128, 0xfffff800, v128
	v_and_b32_e32 v129, 0x3f0, v129
	v_add3_u32 v130, 0, v128, v129
	v_add_u32_e32 v129, 0x400, v130
	v_readfirstlane_b32 s54, v130
	v_add_u32_e32 v128, 0x4000, v130
	s_mov_b32 m0, s54
	v_readfirstlane_b32 s54, v129
	v_lshl_add_u64 v[162:163], v[158:159], 0, s[30:31]
	global_load_lds_dwordx4 v[158:159], off
	s_mov_b32 m0, s54
	v_readfirstlane_b32 s54, v128
	v_add_u32_e32 v128, 0x4400, v130
	global_load_lds_dwordx4 v[162:163], off
	s_mov_b32 m0, s54
	v_readfirstlane_b32 s54, v128
	v_add_u32_e32 v131, 0x8000, v130
	global_load_lds_dwordx4 v[160:161], off
	s_mov_b32 m0, s54
	v_readfirstlane_b32 s54, v131
	v_add_u32_e32 v131, 0x8400, v130
	global_load_lds_dwordx4 v[164:165], off
	v_add_u32_e32 v172, 0xc000, v130
	v_lshl_add_u64 v[128:129], v[158:159], 0, 64
	s_mov_b32 m0, s54
	v_readfirstlane_b32 s54, v131
	global_load_lds_dwordx4 v[128:129], off
	v_lshl_add_u64 v[128:129], v[158:159], 0, s[34:35]
	s_mov_b32 m0, s54
	v_readfirstlane_b32 s54, v172
	v_add_u32_e32 v131, 0xc400, v130
	global_load_lds_dwordx4 v[128:129], off
	v_lshl_add_u64 v[128:129], v[160:161], 0, 64
	s_mov_b32 m0, s54
	v_readfirstlane_b32 s54, v131
	v_add_u32_e32 v131, 0x10000, v130
	global_load_lds_dwordx4 v[128:129], off
	v_lshl_add_u64 v[128:129], v[164:165], 0, 64
	s_mov_b32 m0, s54
	v_readfirstlane_b32 s54, v131
	v_add_u32_e32 v131, 0x10400, v130
	global_load_lds_dwordx4 v[128:129], off
	v_add_u32_e32 v172, 0x14000, v130
	v_lshl_add_u64 v[128:129], v[158:159], 0, s[36:37]
	s_mov_b32 m0, s54
	v_readfirstlane_b32 s54, v131
	global_load_lds_dwordx4 v[128:129], off
	v_lshl_add_u64 v[128:129], v[158:159], 0, s[38:39]
	s_mov_b32 m0, s54
	v_readfirstlane_b32 s54, v172
	v_or_b32_e32 v172, 16, v166
	global_load_lds_dwordx4 v[128:129], off
	v_lshl_add_u64 v[128:129], v[160:161], 0, s[36:37]
	s_mov_b32 m0, s54
	v_ashrrev_i32_e32 v173, 31, v172
	global_load_lds_dwordx4 v[128:129], off
	v_lshlrev_b64 v[128:129], 12, v[172:173]
	v_lshl_add_u64 v[128:129], s[12:13], 0, v[128:129]
	v_lshl_add_u64 v[174:175], v[128:129], 0, v[156:157]
	global_load_dwordx4 v[180:183], v[174:175], off offset:2048
	global_load_dwordx4 v[184:187], v[174:175], off
	v_add_u32_e32 v130, 0x14400, v130
	v_lshl_add_u64 v[128:129], v[164:165], 0, s[36:37]
	v_readfirstlane_b32 s54, v130
	s_waitcnt vmcnt(0)
; __device__ __forceinline__ float frcp(float x) { return __builtin_amdgcn_rcpf(x); }
; __device__ __forceinline__ float bf2f(u16 h) { return __uint_as_float(((unsigned)h) << 16); }
; __device__ __forceinline__ void merge_phase(const Params& p, int first, int step, int n, char* lds) {
;     ...
; #pragma unroll
;     for (int i = 0; i < 8; ++i) {
;       const int m = mt * 256 + wm * 128 + i * 16 + lr;
;       const int n0 = nt * 256 + wn * 64 + lq * 16;
;       union { uint4 v[2]; u16 e[16]; } gh, gn;
;       gh.v[0] = *(const uint4*)(gates + (size_t)m * 2048 + n0); gh.v[1] = *(const uint4*)(gates + (size_t)m * 2048 + n0 + 8);
;       gn.v[0] = *(const uint4*)(gates + (size_t)m * 2048 + 1024 + n0); gn.v[1] = *(const uint4*)(gates + (size_t)m * 2048 + 1024 + n0 + 8);
; #pragma unroll
;       for (int j = 0; j < 4; ++j)
; #pragma unroll
;         for (int e = 0; e < 4; ++e) acc[i][j][e] *= bf2f(gh.e[j * 4 + e]) * frcp(bf2f(gn.e[j * 4 + e]));
;     }
	v_lshlrev_b32_e32 v130, 16, v136
	v_and_b32_e32 v131, 0xffff0000, v136
	v_rcp_f32_e32 v130, v130
	v_rcp_f32_e32 v131, v131
	s_mov_b32 m0, s54
	v_and_b32_e32 v136, 0xffff0000, v139
	global_load_lds_dwordx4 v[128:129], off
	v_and_b32_e32 v129, 0xffff0000, v144
	v_lshlrev_b32_e32 v128, 16, v144
	v_pk_mul_f32 v[128:129], v[130:131], v[128:129]
	v_lshlrev_b32_e32 v130, 16, v137
	v_and_b32_e32 v131, 0xffff0000, v137
	v_rcp_f32_e32 v130, v130
	v_rcp_f32_e32 v131, v131
	v_pk_mul_f32 v[0:1], v[0:1], v[128:129]
	v_and_b32_e32 v129, 0xffff0000, v145
	v_lshlrev_b32_e32 v128, 16, v145
	v_pk_mul_f32 v[128:129], v[130:131], v[128:129]
	v_lshlrev_b32_e32 v130, 16, v138
	v_and_b32_e32 v131, 0xffff0000, v138
	v_rcp_f32_e32 v130, v130
	v_rcp_f32_e32 v131, v131
	v_pk_mul_f32 v[2:3], v[2:3], v[128:129]
	v_and_b32_e32 v129, 0xffff0000, v146
	v_lshlrev_b32_e32 v128, 16, v146
	v_pk_mul_f32 v[128:129], v[130:131], v[128:129]
	v_rcp_f32_e32 v145, v136
	v_pk_mul_f32 v[4:5], v[4:5], v[128:129]
	v_lshlrev_b32_e32 v128, 16, v139
	v_rcp_f32_e32 v144, v128
	global_load_dwordx4 v[128:131], v[174:175], off offset:2064
	global_load_dwordx4 v[136:139], v[174:175], off offset:16
	v_lshlrev_b32_e32 v146, 16, v132
	v_and_b32_e32 v132, 0xffff0000, v132
	v_and_b32_e32 v177, 0xffff0000, v147
	v_lshlrev_b32_e32 v176, 16, v147
	v_rcp_f32_e32 v146, v146
	v_rcp_f32_e32 v147, v132
	v_pk_mul_f32 v[144:145], v[144:145], v[176:177]
	v_lshlrev_b32_e32 v132, 16, v133
	v_and_b32_e32 v133, 0xffff0000, v133
	v_pk_mul_f32 v[6:7], v[6:7], v[144:145]
	v_and_b32_e32 v145, 0xffff0000, v140
	v_lshlrev_b32_e32 v144, 16, v140
	v_rcp_f32_e32 v132, v132
	v_rcp_f32_e32 v133, v133
	v_pk_mul_f32 v[144:145], v[146:147], v[144:145]
	v_lshlrev_b32_e32 v140, 16, v134
	v_and_b32_e32 v134, 0xffff0000, v134
	v_pk_mul_f32 v[16:17], v[16:17], v[144:145]
	v_and_b32_e32 v145, 0xffff0000, v141
	v_lshlrev_b32_e32 v144, 16, v141
	v_rcp_f32_e32 v140, v140
	v_rcp_f32_e32 v141, v134
	v_pk_mul_f32 v[132:133], v[132:133], v[144:145]
	v_or_b32_e32 v176, 32, v166
	v_pk_mul_f32 v[18:19], v[18:19], v[132:133]
	v_and_b32_e32 v133, 0xffff0000, v142
	v_lshlrev_b32_e32 v132, 16, v142
	v_ashrrev_i32_e32 v177, 31, v176
	v_pk_mul_f32 v[132:133], v[140:141], v[132:133]
	v_lshlrev_b64 v[140:141], 12, v[176:177]
	v_lshl_add_u64 v[140:141], s[12:13], 0, v[140:141]
	v_lshl_add_u64 v[178:179], v[140:141], 0, v[156:157]
	global_load_dwordx4 v[144:147], v[178:179], off offset:2048
	v_pk_mul_f32 v[12:13], v[12:13], v[132:133]
	v_lshlrev_b32_e32 v132, 16, v135
	v_and_b32_e32 v133, 0xffff0000, v135
	v_rcp_f32_e32 v132, v132
	v_rcp_f32_e32 v133, v133
	global_load_dwordx4 v[188:191], v[178:179], off
	v_and_b32_e32 v135, 0xffff0000, v143
	v_lshlrev_b32_e32 v134, 16, v143
	v_pk_mul_f32 v[132:133], v[132:133], v[134:135]
	v_lshlrev_b32_e32 v134, 16, v180
	v_and_b32_e32 v135, 0xffff0000, v180
	v_rcp_f32_e32 v134, v134
	v_rcp_f32_e32 v135, v135
	v_pk_mul_f32 v[14:15], v[14:15], v[132:133]
	v_and_b32_e32 v133, 0xffff0000, v184
	v_lshlrev_b32_e32 v132, 16, v184
	v_pk_mul_f32 v[132:133], v[134:135], v[132:133]
	v_lshlrev_b32_e32 v134, 16, v181
	v_and_b32_e32 v135, 0xffff0000, v181
	v_rcp_f32_e32 v134, v134
	v_rcp_f32_e32 v135, v135
	v_pk_mul_f32 v[20:21], v[20:21], v[132:133]
	v_and_b32_e32 v133, 0xffff0000, v185
	v_lshlrev_b32_e32 v132, 16, v185
	v_pk_mul_f32 v[132:133], v[134:135], v[132:133]
	v_lshlrev_b32_e32 v134, 16, v182
	v_and_b32_e32 v135, 0xffff0000, v182
	v_rcp_f32_e32 v134, v134
	v_rcp_f32_e32 v135, v135
	v_pk_mul_f32 v[22:23], v[22:23], v[132:133]
	v_and_b32_e32 v133, 0xffff0000, v186
	v_lshlrev_b32_e32 v132, 16, v186
	v_pk_mul_f32 v[132:133], v[134:135], v[132:133]
	v_and_b32_e32 v140, 0xffff0000, v183
	v_pk_mul_f32 v[28:29], v[28:29], v[132:133]
	v_lshlrev_b32_e32 v132, 16, v183
	v_rcp_f32_e32 v180, v132
	global_load_dwordx4 v[132:135], v[178:179], off offset:2064
	v_rcp_f32_e32 v181, v140
	global_load_dwordx4 v[140:143], v[178:179], off offset:16
	v_and_b32_e32 v183, 0xffff0000, v187
	v_lshlrev_b32_e32 v182, 16, v187
	v_pk_mul_f32 v[180:181], v[180:181], v[182:183]
	v_or_b32_e32 v184, 64, v166
	v_pk_mul_f32 v[30:31], v[30:31], v[180:181]
	s_waitcnt vmcnt(0)
	v_lshlrev_b32_e32 v182, 16, v128
	v_and_b32_e32 v128, 0xffff0000, v128
	v_rcp_f32_e32 v182, v182
	v_rcp_f32_e32 v183, v128
	v_lshlrev_b32_e32 v128, 16, v129
	v_and_b32_e32 v129, 0xffff0000, v129
	v_and_b32_e32 v181, 0xffff0000, v136
	v_lshlrev_b32_e32 v180, 16, v136
	v_rcp_f32_e32 v128, v128
	v_rcp_f32_e32 v129, v129
	v_pk_mul_f32 v[180:181], v[182:183], v[180:181]
	v_lshlrev_b32_e32 v136, 16, v130
	v_and_b32_e32 v130, 0xffff0000, v130
	v_pk_mul_f32 v[48:49], v[48:49], v[180:181]
	v_and_b32_e32 v181, 0xffff0000, v137
	v_lshlrev_b32_e32 v180, 16, v137
	v_rcp_f32_e32 v136, v136
	v_rcp_f32_e32 v137, v130
	v_pk_mul_f32 v[128:129], v[128:129], v[180:181]
	v_or_b32_e32 v180, 48, v166
	v_pk_mul_f32 v[50:51], v[50:51], v[128:129]
	v_and_b32_e32 v129, 0xffff0000, v138
	v_lshlrev_b32_e32 v128, 16, v138
	v_ashrrev_i32_e32 v181, 31, v180
	v_pk_mul_f32 v[128:129], v[136:137], v[128:129]
	v_lshlrev_b64 v[136:137], 12, v[180:181]
	v_lshl_add_u64 v[136:137], s[12:13], 0, v[136:137]
	v_lshl_add_u64 v[182:183], v[136:137], 0, v[156:157]
	global_load_dwordx4 v[192:195], v[182:183], off offset:2048
	global_load_dwordx4 v[214:217], v[182:183], off
	v_pk_mul_f32 v[40:41], v[40:41], v[128:129]
	v_lshlrev_b32_e32 v128, 16, v131
	v_and_b32_e32 v129, 0xffff0000, v131
	v_rcp_f32_e32 v128, v128
	v_rcp_f32_e32 v129, v129
	v_and_b32_e32 v131, 0xffff0000, v139
	v_lshlrev_b32_e32 v130, 16, v139
	v_and_b32_e32 v136, 0xffff0000, v147
	v_pk_mul_f32 v[128:129], v[128:129], v[130:131]
	v_lshlrev_b32_e32 v130, 16, v144
; __device__ __forceinline__ float frcp(float x) { return __builtin_amdgcn_rcpf(x); }
; __device__ __forceinline__ float bf2f(u16 h) { return __uint_as_float(((unsigned)h) << 16); }
; __device__ __forceinline__ void merge_phase(const Params& p, int first, int step, int n, char* lds) {
;     ...
; #pragma unroll
;     for (int i = 0; i < 8; ++i) {
;       const int m = mt * 256 + wm * 128 + i * 16 + lr;
;       const int n0 = nt * 256 + wn * 64 + lq * 16;
;       union { uint4 v[2]; u16 e[16]; } gh, gn;
;       gh.v[0] = *(const uint4*)(gates + (size_t)m * 2048 + n0); gh.v[1] = *(const uint4*)(gates + (size_t)m * 2048 + n0 + 8);
;       gn.v[0] = *(const uint4*)(gates + (size_t)m * 2048 + 1024 + n0); gn.v[1] = *(const uint4*)(gates + (size_t)m * 2048 + 1024 + n0 + 8);
; #pragma unroll
;       for (int j = 0; j < 4; ++j)
; #pragma unroll
;         for (int e = 0; e < 4; ++e) acc[i][j][e] *= bf2f(gh.e[j * 4 + e]) * frcp(bf2f(gn.e[j * 4 + e]));
;     }
	v_and_b32_e32 v131, 0xffff0000, v144
	v_rcp_f32_e32 v130, v130
	v_rcp_f32_e32 v131, v131
	v_pk_mul_f32 v[42:43], v[42:43], v[128:129]
	v_and_b32_e32 v129, 0xffff0000, v188
	v_lshlrev_b32_e32 v128, 16, v188
	v_pk_mul_f32 v[128:129], v[130:131], v[128:129]
	v_lshlrev_b32_e32 v130, 16, v145
	v_and_b32_e32 v131, 0xffff0000, v145
	v_rcp_f32_e32 v130, v130
	v_rcp_f32_e32 v131, v131
	v_pk_mul_f32 v[52:53], v[52:53], v[128:129]
	v_and_b32_e32 v129, 0xffff0000, v189
	v_lshlrev_b32_e32 v128, 16, v189
	v_pk_mul_f32 v[128:129], v[130:131], v[128:129]
	v_lshlrev_b32_e32 v130, 16, v146
	v_and_b32_e32 v131, 0xffff0000, v146
	v_rcp_f32_e32 v130, v130
	v_rcp_f32_e32 v131, v131
	v_pk_mul_f32 v[54:55], v[54:55], v[128:129]
	v_and_b32_e32 v129, 0xffff0000, v190
	v_lshlrev_b32_e32 v128, 16, v190
	v_pk_mul_f32 v[128:129], v[130:131], v[128:129]
	v_rcp_f32_e32 v145, v136
	v_pk_mul_f32 v[56:57], v[56:57], v[128:129]
	v_lshlrev_b32_e32 v128, 16, v147
	v_rcp_f32_e32 v144, v128
	global_load_dwordx4 v[128:131], v[182:183], off offset:2064
	global_load_dwordx4 v[136:139], v[182:183], off offset:16
	v_and_b32_e32 v147, 0xffff0000, v191
	v_lshlrev_b32_e32 v146, 16, v191
	v_pk_mul_f32 v[144:145], v[144:145], v[146:147]
	v_lshlrev_b32_e32 v146, 16, v132
	v_and_b32_e32 v132, 0xffff0000, v132
	v_rcp_f32_e32 v146, v146
	v_rcp_f32_e32 v147, v132
	v_lshlrev_b32_e32 v132, 16, v133
	v_and_b32_e32 v133, 0xffff0000, v133
	v_pk_mul_f32 v[58:59], v[58:59], v[144:145]
	v_and_b32_e32 v145, 0xffff0000, v140
	v_lshlrev_b32_e32 v144, 16, v140
	v_rcp_f32_e32 v132, v132
	v_rcp_f32_e32 v133, v133
	v_pk_mul_f32 v[144:145], v[146:147], v[144:145]
	v_lshlrev_b32_e32 v140, 16, v134
	v_and_b32_e32 v134, 0xffff0000, v134
	v_pk_mul_f32 v[72:73], v[72:73], v[144:145]
	v_and_b32_e32 v145, 0xffff0000, v141
	v_lshlrev_b32_e32 v144, 16, v141
	v_rcp_f32_e32 v140, v140
	v_rcp_f32_e32 v141, v134
	v_pk_mul_f32 v[132:133], v[132:133], v[144:145]
	v_ashrrev_i32_e32 v185, 31, v184
	v_pk_mul_f32 v[74:75], v[74:75], v[132:133]
	v_and_b32_e32 v133, 0xffff0000, v142
	v_lshlrev_b32_e32 v132, 16, v142
	v_pk_mul_f32 v[132:133], v[140:141], v[132:133]
	v_lshlrev_b64 v[140:141], 12, v[184:185]
	v_lshl_add_u64 v[140:141], s[12:13], 0, v[140:141]
	v_lshl_add_u64 v[186:187], v[140:141], 0, v[156:157]
	global_load_dwordx4 v[218:221], v[186:187], off offset:2048
	v_pk_mul_f32 v[68:69], v[68:69], v[132:133]
	v_lshlrev_b32_e32 v132, 16, v135
	v_and_b32_e32 v133, 0xffff0000, v135
	v_rcp_f32_e32 v132, v132
	v_rcp_f32_e32 v133, v133
	global_load_dwordx4 v[222:225], v[186:187], off
	v_and_b32_e32 v135, 0xffff0000, v143
	v_lshlrev_b32_e32 v134, 16, v143
	v_pk_mul_f32 v[132:133], v[132:133], v[134:135]
	s_waitcnt vmcnt(0)
	v_lshlrev_b32_e32 v134, 16, v192
	v_and_b32_e32 v135, 0xffff0000, v192
	v_rcp_f32_e32 v134, v134
	v_rcp_f32_e32 v135, v135
	v_pk_mul_f32 v[70:71], v[70:71], v[132:133]
	v_and_b32_e32 v133, 0xffff0000, v214
	v_lshlrev_b32_e32 v132, 16, v214
	v_pk_mul_f32 v[132:133], v[134:135], v[132:133]
	v_lshlrev_b32_e32 v134, 16, v193
	v_and_b32_e32 v135, 0xffff0000, v193
	v_rcp_f32_e32 v134, v134
	v_rcp_f32_e32 v135, v135
	v_pk_mul_f32 v[76:77], v[76:77], v[132:133]
	v_and_b32_e32 v133, 0xffff0000, v215
	v_lshlrev_b32_e32 v132, 16, v215
	v_pk_mul_f32 v[132:133], v[134:135], v[132:133]
	v_lshlrev_b32_e32 v134, 16, v194
	v_and_b32_e32 v135, 0xffff0000, v194
	v_rcp_f32_e32 v134, v134
	v_rcp_f32_e32 v135, v135
	v_pk_mul_f32 v[78:79], v[78:79], v[132:133]
	v_and_b32_e32 v133, 0xffff0000, v216
	v_lshlrev_b32_e32 v132, 16, v216
	v_pk_mul_f32 v[132:133], v[134:135], v[132:133]
	global_load_dwordx4 v[142:145], v[186:187], off offset:16
	v_pk_mul_f32 v[80:81], v[80:81], v[132:133]
	v_lshlrev_b32_e32 v132, 16, v195
	v_rcp_f32_e32 v140, v132
	global_load_dwordx4 v[132:135], v[186:187], off offset:2064
	v_and_b32_e32 v141, 0xffff0000, v195
	v_rcp_f32_e32 v141, v141
	v_and_b32_e32 v147, 0xffff0000, v217
	v_lshlrev_b32_e32 v146, 16, v217
	v_or_b32_e32 v188, 0x50, v166
	v_pk_mul_f32 v[140:141], v[140:141], v[146:147]
	v_ashrrev_i32_e32 v189, 31, v188
	v_pk_mul_f32 v[82:83], v[82:83], v[140:141]
	v_lshlrev_b32_e32 v146, 16, v128
	v_and_b32_e32 v128, 0xffff0000, v128
	v_rcp_f32_e32 v146, v146
	v_rcp_f32_e32 v147, v128
	v_lshlrev_b32_e32 v128, 16, v129
	v_and_b32_e32 v129, 0xffff0000, v129
	v_and_b32_e32 v141, 0xffff0000, v136
	v_lshlrev_b32_e32 v140, 16, v136
	v_rcp_f32_e32 v128, v128
	v_rcp_f32_e32 v129, v129
	v_pk_mul_f32 v[140:141], v[146:147], v[140:141]
	v_lshlrev_b32_e32 v136, 16, v130
	v_and_b32_e32 v130, 0xffff0000, v130
	v_pk_mul_f32 v[100:101], v[100:101], v[140:141]
	v_and_b32_e32 v141, 0xffff0000, v137
	v_lshlrev_b32_e32 v140, 16, v137
	v_rcp_f32_e32 v136, v136
	v_rcp_f32_e32 v137, v130
	v_pk_mul_f32 v[128:129], v[128:129], v[140:141]
	v_lshlrev_b32_e32 v130, 16, v139
	v_pk_mul_f32 v[102:103], v[102:103], v[128:129]
	v_and_b32_e32 v129, 0xffff0000, v138
	v_lshlrev_b32_e32 v128, 16, v138
	v_pk_mul_f32 v[128:129], v[136:137], v[128:129]
	v_lshlrev_b64 v[136:137], 12, v[188:189]
	v_lshl_add_u64 v[136:137], s[12:13], 0, v[136:137]
	v_lshl_add_u64 v[190:191], v[136:137], 0, v[156:157]
	global_load_dwordx4 v[214:217], v[190:191], off offset:2048
	v_pk_mul_f32 v[96:97], v[96:97], v[128:129]
	v_lshlrev_b32_e32 v128, 16, v131
	v_and_b32_e32 v129, 0xffff0000, v131
	v_rcp_f32_e32 v128, v128
	v_rcp_f32_e32 v129, v129
	global_load_dwordx4 v[226:229], v[190:191], off
	v_and_b32_e32 v131, 0xffff0000, v139
	v_and_b32_e32 v136, 0xffff0000, v221
	v_pk_mul_f32 v[128:129], v[128:129], v[130:131]
	v_lshlrev_b32_e32 v130, 16, v218
	v_and_b32_e32 v131, 0xffff0000, v218
	v_rcp_f32_e32 v130, v130
	v_rcp_f32_e32 v131, v131
	v_pk_mul_f32 v[98:99], v[98:99], v[128:129]
	v_and_b32_e32 v129, 0xffff0000, v222
	v_lshlrev_b32_e32 v128, 16, v222
	v_pk_mul_f32 v[128:129], v[130:131], v[128:129]
	v_lshlrev_b32_e32 v130, 16, v219
	v_and_b32_e32 v131, 0xffff0000, v219
	v_rcp_f32_e32 v130, v130
	v_rcp_f32_e32 v131, v131
	v_pk_mul_f32 v[104:105], v[104:105], v[128:129]
	v_and_b32_e32 v129, 0xffff0000, v223
	v_lshlrev_b32_e32 v128, 16, v223
	v_pk_mul_f32 v[128:129], v[130:131], v[128:129]
	v_lshlrev_b32_e32 v130, 16, v220
	v_and_b32_e32 v131, 0xffff0000, v220
	v_rcp_f32_e32 v130, v130
	v_rcp_f32_e32 v131, v131
	v_pk_mul_f32 v[106:107], v[106:107], v[128:129]
	v_and_b32_e32 v129, 0xffff0000, v224
	v_lshlrev_b32_e32 v128, 16, v224
	v_pk_mul_f32 v[128:129], v[130:131], v[128:129]
	v_rcp_f32_e32 v141, v136
	v_pk_mul_f32 v[108:109], v[108:109], v[128:129]
	v_lshlrev_b32_e32 v128, 16, v221
	v_rcp_f32_e32 v140, v128
	global_load_dwordx4 v[128:131], v[190:191], off offset:2064
	global_load_dwordx4 v[136:139], v[190:191], off offset:16
	v_and_b32_e32 v147, 0xffff0000, v225
	v_lshlrev_b32_e32 v146, 16, v225
	v_pk_mul_f32 v[140:141], v[140:141], v[146:147]
	v_or_b32_e32 v192, 0x60, v166
	s_waitcnt vmcnt(0)
; __device__ __forceinline__ float frcp(float x) { return __builtin_amdgcn_rcpf(x); }
; __device__ __forceinline__ float bf2f(u16 h) { return __uint_as_float(((unsigned)h) << 16); }
; __device__ __forceinline__ void merge_phase(const Params& p, int first, int step, int n, char* lds) {
;     ...
; #pragma unroll
;     for (int i = 0; i < 8; ++i) {
;       const int m = mt * 256 + wm * 128 + i * 16 + lr;
;       const int n0 = nt * 256 + wn * 64 + lq * 16;
;       union { uint4 v[2]; u16 e[16]; } gh, gn;
;       gh.v[0] = *(const uint4*)(gates + (size_t)m * 2048 + n0); gh.v[1] = *(const uint4*)(gates + (size_t)m * 2048 + n0 + 8);
;       gn.v[0] = *(const uint4*)(gates + (size_t)m * 2048 + 1024 + n0); gn.v[1] = *(const uint4*)(gates + (size_t)m * 2048 + 1024 + n0 + 8);
; #pragma unroll
;       for (int j = 0; j < 4; ++j)
; #pragma unroll
;         for (int e = 0; e < 4; ++e) acc[i][j][e] *= bf2f(gh.e[j * 4 + e]) * frcp(bf2f(gn.e[j * 4 + e]));
;     }
	v_lshlrev_b32_e32 v146, 16, v132
	v_and_b32_e32 v132, 0xffff0000, v132
	v_rcp_f32_e32 v146, v146
	v_rcp_f32_e32 v147, v132
	v_lshlrev_b32_e32 v132, 16, v133
	v_and_b32_e32 v133, 0xffff0000, v133
	v_rcp_f32_e32 v132, v132
	v_rcp_f32_e32 v133, v133
	v_pk_mul_f32 v[110:111], v[110:111], v[140:141]
	v_and_b32_e32 v141, 0xffff0000, v142
	v_lshlrev_b32_e32 v140, 16, v142
	v_pk_mul_f32 v[140:141], v[146:147], v[140:141]
	v_ashrrev_i32_e32 v193, 31, v192
	v_pk_mul_f32 v[120:121], v[120:121], v[140:141]
	v_and_b32_e32 v141, 0xffff0000, v143
	v_lshlrev_b32_e32 v140, 16, v143
	v_pk_mul_f32 v[132:133], v[132:133], v[140:141]
	v_lshlrev_b32_e32 v140, 16, v134
	v_and_b32_e32 v134, 0xffff0000, v134
	v_rcp_f32_e32 v140, v140
	v_rcp_f32_e32 v141, v134
	v_pk_mul_f32 v[122:123], v[122:123], v[132:133]
	v_and_b32_e32 v133, 0xffff0000, v144
	v_lshlrev_b32_e32 v132, 16, v144
	v_pk_mul_f32 v[132:133], v[140:141], v[132:133]
	v_and_b32_e32 v219, 0xffff0000, v145
	v_pk_mul_f32 v[116:117], v[116:117], v[132:133]
	v_lshlrev_b32_e32 v132, 16, v135
	v_rcp_f32_e32 v146, v132
	v_lshlrev_b64 v[132:133], 12, v[192:193]
	v_lshl_add_u64 v[132:133], s[12:13], 0, v[132:133]
	v_lshl_add_u64 v[194:195], v[132:133], 0, v[156:157]
	global_load_dwordx4 v[140:143], v[194:195], off offset:2048
	v_and_b32_e32 v132, 0xffff0000, v135
	v_rcp_f32_e32 v147, v132
	global_load_dwordx4 v[132:135], v[194:195], off
	v_lshlrev_b32_e32 v218, 16, v145
	v_and_b32_e32 v213, 0xffff0000, v217
	v_pk_mul_f32 v[144:145], v[146:147], v[218:219]
	v_lshlrev_b32_e32 v146, 16, v214
	v_and_b32_e32 v147, 0xffff0000, v214
	v_rcp_f32_e32 v146, v146
	v_rcp_f32_e32 v147, v147
	v_pk_mul_f32 v[118:119], v[118:119], v[144:145]
	v_and_b32_e32 v145, 0xffff0000, v226
	v_lshlrev_b32_e32 v144, 16, v226
	v_pk_mul_f32 v[144:145], v[146:147], v[144:145]
	v_lshlrev_b32_e32 v146, 16, v215
	v_and_b32_e32 v147, 0xffff0000, v215
	v_rcp_f32_e32 v146, v146
	v_rcp_f32_e32 v147, v147
	v_pk_mul_f32 v[124:125], v[124:125], v[144:145]
	v_and_b32_e32 v145, 0xffff0000, v227
	v_lshlrev_b32_e32 v144, 16, v227
	v_pk_mul_f32 v[144:145], v[146:147], v[144:145]
	v_lshlrev_b32_e32 v146, 16, v216
	v_and_b32_e32 v147, 0xffff0000, v216
	v_rcp_f32_e32 v146, v146
	v_rcp_f32_e32 v147, v147
	v_pk_mul_f32 v[126:127], v[126:127], v[144:145]
	v_and_b32_e32 v145, 0xffff0000, v228
	v_lshlrev_b32_e32 v144, 16, v228
	v_pk_mul_f32 v[144:145], v[146:147], v[144:145]
	v_rcp_f32_e32 v219, v213
	v_pk_mul_f32 v[112:113], v[112:113], v[144:145]
	v_lshlrev_b32_e32 v144, 16, v217
	v_rcp_f32_e32 v218, v144
	global_load_dwordx4 v[144:147], v[194:195], off offset:2064
	global_load_dwordx4 v[214:217], v[194:195], off offset:16
	v_and_b32_e32 v221, 0xffff0000, v229
	v_lshlrev_b32_e32 v220, 16, v229
	v_pk_mul_f32 v[218:219], v[218:219], v[220:221]
	s_and_b32 s47, s70, 0xffffff00
	v_pk_mul_f32 v[114:115], v[114:115], v[218:219]
	v_lshlrev_b32_e32 v213, 16, v128
	v_and_b32_e32 v128, 0xffff0000, v128
	v_rcp_f32_e32 v220, v213
	v_rcp_f32_e32 v221, v128
	v_lshlrev_b32_e32 v128, 16, v129
	v_and_b32_e32 v129, 0xffff0000, v129
	v_rcp_f32_e32 v128, v128
	v_rcp_f32_e32 v129, v129
	v_and_b32_e32 v219, 0xffff0000, v136
	v_lshlrev_b32_e32 v218, 16, v136
	v_pk_mul_f32 v[218:219], v[220:221], v[218:219]
	s_and_b32 s46, s69, 0x300
	v_pk_mul_f32 v[92:93], v[92:93], v[218:219]
	v_and_b32_e32 v219, 0xffff0000, v137
	v_lshlrev_b32_e32 v218, 16, v137
	v_pk_mul_f32 v[222:223], v[128:129], v[218:219]
	v_lshlrev_b32_e32 v128, 16, v130
	v_rcp_f32_e32 v224, v128
	v_and_b32_e32 v128, 0xffff0000, v130
	v_rcp_f32_e32 v225, v128
	v_or_b32_e32 v128, 0x70, v166
	v_ashrrev_i32_e32 v129, 31, v128
	v_lshlrev_b64 v[136:137], 12, v[128:129]
	v_lshl_add_u64 v[136:137], s[12:13], 0, v[136:137]
	v_lshl_add_u64 v[136:137], v[136:137], 0, v[156:157]
	global_load_dwordx4 v[218:221], v[136:137], off offset:2048
	v_pk_mul_f32 v[94:95], v[94:95], v[222:223]
	v_and_b32_e32 v223, 0xffff0000, v138
	v_lshlrev_b32_e32 v222, 16, v138
	v_pk_mul_f32 v[226:227], v[224:225], v[222:223]
	global_load_dwordx4 v[222:225], v[136:137], off
	v_lshlrev_b32_e32 v130, 16, v131
	v_and_b32_e32 v131, 0xffff0000, v131
	v_rcp_f32_e32 v130, v130
	v_rcp_f32_e32 v131, v131
	v_pk_mul_f32 v[88:89], v[88:89], v[226:227]
	v_and_b32_e32 v227, 0xffff0000, v139
	v_lshlrev_b32_e32 v226, 16, v139
	s_waitcnt vmcnt(0)
; __device__ __forceinline__ int otid() { int t = threadIdx.x; asm volatile("" : "+v"(t)); return t; }
; __device__ __forceinline__ float frcp(float x) { return __builtin_amdgcn_rcpf(x); }
; __device__ __forceinline__ float bf2f(u16 h) { return __uint_as_float(((unsigned)h) << 16); }
; template <bool SWAP>
; __device__ __forceinline__ void gemm_main(f32x4 (&acc)[8][4], const TP& t, int nk, char* lds) {
;   const u16* a0 = t.a0; const u16* a1 = t.a1; const u16* b0 = t.b0; const u16* b1 = t.b1;
;   const int tid = otid(), lane = tid & 63, wave = tid >> 6;
;   const int wm = wave >> 2, wn = wave & 3, lr = lane & 15, lq = lane >> 4;
;   const int ldoff = wave * 2048 + lane * 16;
;   const int sw = (lq ^ ((0 - (lr >> 2)) & 3)) << 4;
;   const int aoff = (wm * 128 + lr) * 64 + sw, boff = T_ASTAGE + (wn * 64 + lr) * 64 + sw;
; __device__ __forceinline__ void merge_phase(const Params& p, int first, int step, int n, char* lds) {
;     ...
; #pragma unroll
;       for (int j = 0; j < 4; ++j)
; #pragma unroll
;         for (int e = 0; e < 4; ++e) acc[i][j][e] *= bf2f(gh.e[j * 4 + e]) * frcp(bf2f(gn.e[j * 4 + e]));
;     }
;     gemm_main<true>(acc, cur, 16, lds);
	v_lshlrev_b32_e32 v138, 16, v140
	v_and_b32_e32 v139, 0xffff0000, v140
	v_rcp_f32_e32 v138, v138
	v_rcp_f32_e32 v139, v139
	v_pk_mul_f32 v[130:131], v[130:131], v[226:227]
	v_and_b32_e32 v229, 0xffff0000, v134
	v_pk_mul_f32 v[90:91], v[90:91], v[130:131]
	v_and_b32_e32 v131, 0xffff0000, v132
	v_lshlrev_b32_e32 v130, 16, v132
	v_lshlrev_b32_e32 v132, 16, v141
	v_pk_mul_f32 v[130:131], v[138:139], v[130:131]
	v_rcp_f32_e32 v138, v132
	v_and_b32_e32 v132, 0xffff0000, v141
	v_rcp_f32_e32 v139, v132
	v_pk_mul_f32 v[84:85], v[84:85], v[130:131]
	v_and_b32_e32 v131, 0xffff0000, v133
	v_lshlrev_b32_e32 v130, 16, v133
	v_pk_mul_f32 v[130:131], v[138:139], v[130:131]
	v_lshlrev_b32_e32 v138, 16, v142
	v_pk_mul_f32 v[86:87], v[86:87], v[130:131]
	global_load_dwordx4 v[130:133], v[136:137], off offset:2064
	v_rcp_f32_e32 v226, v138
	v_and_b32_e32 v138, 0xffff0000, v142
	v_rcp_f32_e32 v227, v138
	global_load_dwordx4 v[138:141], v[136:137], off offset:16
	v_lshlrev_b32_e32 v228, 16, v134
	v_lshlrev_b32_e32 v134, 16, v143
	v_rcp_f32_e32 v142, v134
	v_and_b32_e32 v134, 0xffff0000, v143
	v_rcp_f32_e32 v143, v134
	v_pk_mul_f32 v[226:227], v[226:227], v[228:229]
	s_mov_b32 s54, 0x18000
	v_pk_mul_f32 v[64:65], v[64:65], v[226:227]
	v_and_b32_e32 v227, 0xffff0000, v135
	v_lshlrev_b32_e32 v226, 16, v135
	v_pk_mul_f32 v[134:135], v[142:143], v[226:227]
	v_lshlrev_b32_e32 v142, 16, v144
	v_and_b32_e32 v143, 0xffff0000, v144
	v_rcp_f32_e32 v142, v142
	v_rcp_f32_e32 v143, v143
	v_pk_mul_f32 v[66:67], v[66:67], v[134:135]
	v_and_b32_e32 v135, 0xffff0000, v214
	v_lshlrev_b32_e32 v134, 16, v214
	v_pk_mul_f32 v[134:135], v[142:143], v[134:135]
	v_lshlrev_b32_e32 v142, 16, v145
	v_and_b32_e32 v143, 0xffff0000, v145
	v_rcp_f32_e32 v142, v142
	v_rcp_f32_e32 v143, v143
	v_pk_mul_f32 v[60:61], v[60:61], v[134:135]
	v_and_b32_e32 v135, 0xffff0000, v215
	v_lshlrev_b32_e32 v134, 16, v215
	v_pk_mul_f32 v[134:135], v[142:143], v[134:135]
	v_lshlrev_b32_e32 v142, 16, v146
	v_and_b32_e32 v143, 0xffff0000, v146
	v_rcp_f32_e32 v142, v142
	v_rcp_f32_e32 v143, v143
	v_pk_mul_f32 v[62:63], v[62:63], v[134:135]
	v_and_b32_e32 v135, 0xffff0000, v216
	v_lshlrev_b32_e32 v134, 16, v216
	v_pk_mul_f32 v[134:135], v[142:143], v[134:135]
	v_lshlrev_b32_e32 v142, 16, v147
	v_and_b32_e32 v143, 0xffff0000, v147
	v_rcp_f32_e32 v142, v142
	v_rcp_f32_e32 v143, v143
	v_pk_mul_f32 v[44:45], v[44:45], v[134:135]
	v_and_b32_e32 v135, 0xffff0000, v217
	v_lshlrev_b32_e32 v134, 16, v217
	v_pk_mul_f32 v[134:135], v[142:143], v[134:135]
	v_lshlrev_b32_e32 v142, 16, v218
	v_and_b32_e32 v143, 0xffff0000, v218
	v_rcp_f32_e32 v142, v142
	v_rcp_f32_e32 v143, v143
	v_pk_mul_f32 v[46:47], v[46:47], v[134:135]
	v_and_b32_e32 v135, 0xffff0000, v222
	v_lshlrev_b32_e32 v134, 16, v222
	v_pk_mul_f32 v[134:135], v[142:143], v[134:135]
	v_lshlrev_b32_e32 v142, 16, v219
	v_and_b32_e32 v143, 0xffff0000, v219
	v_rcp_f32_e32 v142, v142
	v_rcp_f32_e32 v143, v143
	v_pk_mul_f32 v[36:37], v[36:37], v[134:135]
	v_and_b32_e32 v135, 0xffff0000, v223
	v_lshlrev_b32_e32 v134, 16, v223
	v_pk_mul_f32 v[134:135], v[142:143], v[134:135]
	v_lshlrev_b32_e32 v142, 16, v220
	v_and_b32_e32 v143, 0xffff0000, v220
	v_rcp_f32_e32 v142, v142
	v_rcp_f32_e32 v143, v143
	v_pk_mul_f32 v[38:39], v[38:39], v[134:135]
	v_and_b32_e32 v135, 0xffff0000, v224
	v_lshlrev_b32_e32 v134, 16, v224
	v_pk_mul_f32 v[134:135], v[142:143], v[134:135]
	v_lshlrev_b32_e32 v142, 16, v221
	v_and_b32_e32 v143, 0xffff0000, v221
	v_rcp_f32_e32 v142, v142
	v_rcp_f32_e32 v143, v143
	v_pk_mul_f32 v[32:33], v[32:33], v[134:135]
	v_and_b32_e32 v135, 0xffff0000, v225
	v_lshlrev_b32_e32 v134, 16, v225
	v_pk_mul_f32 v[134:135], v[142:143], v[134:135]
	s_waitcnt vmcnt(0)
	v_lshlrev_b32_e32 v142, 16, v130
	v_and_b32_e32 v130, 0xffff0000, v130
	v_rcp_f32_e32 v142, v142
	v_rcp_f32_e32 v143, v130
	v_lshlrev_b32_e32 v130, 16, v131
	v_and_b32_e32 v131, 0xffff0000, v131
	v_rcp_f32_e32 v130, v130
	v_rcp_f32_e32 v131, v131
	v_pk_mul_f32 v[34:35], v[34:35], v[134:135]
	v_and_b32_e32 v135, 0xffff0000, v138
	v_lshlrev_b32_e32 v134, 16, v138
	v_pk_mul_f32 v[134:135], v[142:143], v[134:135]
	v_bitop3_b32 v145, v211, 3, v212 bitop3:0x48
	v_pk_mul_f32 v[24:25], v[24:25], v[134:135]
	v_and_b32_e32 v135, 0xffff0000, v139
	v_lshlrev_b32_e32 v134, 16, v139
	v_pk_mul_f32 v[130:131], v[130:131], v[134:135]
	v_lshlrev_b32_e32 v134, 16, v132
	v_and_b32_e32 v132, 0xffff0000, v132
	v_rcp_f32_e32 v134, v134
	v_rcp_f32_e32 v135, v132
	v_lshlrev_b32_e32 v132, 16, v133
	v_and_b32_e32 v133, 0xffff0000, v133
	v_rcp_f32_e32 v132, v132
	v_rcp_f32_e32 v133, v133
	v_pk_mul_f32 v[26:27], v[26:27], v[130:131]
	v_and_b32_e32 v131, 0xffff0000, v140
	v_lshlrev_b32_e32 v130, 16, v140
	v_pk_mul_f32 v[130:131], v[134:135], v[130:131]
	v_bitop3_b32 v134, v205, 3, v206 bitop3:0x48
	v_pk_mul_f32 v[8:9], v[8:9], v[130:131]
	v_and_b32_e32 v131, 0xffff0000, v141
	v_lshlrev_b32_e32 v130, 16, v141
	v_pk_mul_f32 v[130:131], v[132:133], v[130:131]
	s_nop 0
	v_pk_mul_f32 v[10:11], v[10:11], v[130:131]
	v_mov_b32_e32 v130, v153
	s_nop 0
	v_lshlrev_b32_e32 v133, 2, v130
	v_and_b32_e32 v133, 48, v133
	v_sub_u32_e32 v133, 0, v133
	v_and_b32_e32 v138, 15, v130
	v_lshlrev_b32_e32 v131, 5, v130
	v_lshlrev_b32_e32 v132, 4, v130
	v_bitop3_b32 v139, v130, 48, v133 bitop3:0x48
	v_ashrrev_i32_e32 v140, 1, v130
	v_lshlrev_b32_e32 v130, 6, v130
	v_and_b32_e32 v142, 0x33c0, v130
	v_add_u32_e32 v130, s47, v155
	v_and_b32_e32 v131, 0xfffff800, v131
	v_and_b32_e32 v132, 0x3f0, v132
	v_or_b32_e32 v130, v130, v198
	v_add3_u32 v144, 0, v131, v132
	v_ashrrev_i32_e32 v131, 31, v130
	v_lshlrev_b64 v[130:131], 10, v[130:131]
	v_bitop3_b32 v132, v199, 3, v200 bitop3:0x48
	v_lshl_or_b32 v130, v132, 4, v130
	v_add_u32_e32 v132, s46, v201
	v_or_b32_e32 v132, v132, v202
	v_and_or_b32 v133, v140, s68, v138
	v_or3_b32 v132, v132, v203, v204
	v_lshl_or_b32 v141, v133, 6, v139
	v_ashrrev_i32_e32 v133, 31, v132
	v_lshlrev_b64 v[132:133], 10, v[132:133]
	v_lshl_or_b32 v132, v134, 4, v132
	v_add_u32_e32 v134, s46, v207
	v_or3_b32 v134, v134, v208, v209
	v_or3_b32 v134, v134, v210, 4
	v_ashrrev_i32_e32 v135, 31, v134
	v_lshlrev_b64 v[134:135], 10, v[134:135]
	v_lshl_or_b32 v134, v145, 4, v134
	v_or_b32_e32 v143, v142, v139
	v_lshl_add_u64 v[130:131], s[48:49], 0, v[130:131]
	v_lshl_add_u64 v[132:133], s[26:27], 0, v[132:133]
	v_lshl_add_u64 v[134:135], s[26:27], 0, v[134:135]
	s_mov_b64 s[46:47], 0
	v_readfirstlane_b32 s98, v144
	s_waitcnt vmcnt(8)
	s_barrier
	s_cmp_lt_u32 s98, 0x2000
	s_cbranch_scc1 .Lmg2_top
	s_barrier
	s_setprio 1

; template <class MK, class SW, class EPI>
; __device__ __forceinline__ void gemm_phase(int first, int step, int n, int nk, MK mk, SW swapf, EPI epi, char* lds) {
;     ...
;   TP cur = mk(first);
;   gemm_issue3(cur, lds);
; #pragma unroll 1
;   for (int it = first; it < n; it += step) {
;     const bool has_next = (it + step < n);
;     const TP nxt = mk(has_next ? it + step : it);
;     f32x4 acc[8][4];
;     zero_acc(acc);
;     if (swapf(it)) gemm_main<true>(acc, cur, nk, lds); else gemm_main<false>(acc, cur, nk, lds);
; __device__ __forceinline__ void zero_acc(f32x4 (&acc)[8][4]) {
; #pragma unroll
;   for (int i = 0; i < 8; ++i)
; #pragma unroll
;     for (int j = 0; j < 4; ++j) acc[i][j] = (f32x4){0.f, 0.f, 0.f, 0.f};
; }
.LBB0_938:
	v_mov_b32_e32 v139, v153
	v_mov_b32_e32 v134, v153
	v_mov_b32_e32 v138, v153
	v_mov_b32_e32 v135, v153
	v_mov_b32_e32 v137, v153
	v_mov_b32_e32 v136, v153
	v_mov_b32_e32 v0, v153
	s_mov_b32 s56, s38
	v_lshlrev_b32_e32 v3, 2, v0
	v_and_b32_e32 v3, 48, v3
	v_sub_u32_e32 v3, 0, v3
	v_and_b32_e32 v140, 15, v0
	v_lshlrev_b32_e32 v1, 5, v0
	v_lshlrev_b32_e32 v2, 4, v0
	v_bitop3_b32 v141, v0, 48, v3 bitop3:0x48
	v_ashrrev_i32_e32 v142, 1, v0
	v_lshlrev_b32_e32 v0, 6, v0
	v_and_b32_e32 v1, 0xfffff800, v1
	v_and_b32_e32 v2, 0x3f0, v2
	v_and_or_b32 v3, v142, s54, v140
	v_and_b32_e32 v143, 0x33c0, v0
	v_mov_b32_e32 v0, 0
	v_lshl_or_b32 v144, v3, 6, v141
	v_or_b32_e32 v149, v143, v141
	v_add3_u32 v151, 0, v1, v2
	v_lshl_add_u64 v[128:129], v[146:147], 0, s[26:27]
	v_lshl_add_u64 v[130:131], v[156:157], 0, s[28:29]
	v_lshl_add_u64 v[132:133], v[158:159], 0, s[28:29]
	s_mov_b32 s36, 0x18000
	v_mov_b32_e32 v1, v0
	v_mov_b32_e32 v2, v0
	v_mov_b32_e32 v3, v0
	v_mov_b32_e32 v4, v0
	v_mov_b32_e32 v5, v0
	v_mov_b32_e32 v6, v0
	v_mov_b32_e32 v7, v0
	v_mov_b32_e32 v8, v0
	v_mov_b32_e32 v9, v0
	v_mov_b32_e32 v10, v0
	v_mov_b32_e32 v11, v0
	v_mov_b32_e32 v12, v0
	v_mov_b32_e32 v13, v0
	v_mov_b32_e32 v14, v0
	v_mov_b32_e32 v15, v0
	v_mov_b32_e32 v16, v0
	v_mov_b32_e32 v17, v0
	v_mov_b32_e32 v18, v0
	v_mov_b32_e32 v19, v0
	v_mov_b32_e32 v20, v0
	v_mov_b32_e32 v21, v0
	v_mov_b32_e32 v22, v0
	v_mov_b32_e32 v23, v0
	v_mov_b32_e32 v24, v0
	v_mov_b32_e32 v25, v0
	v_mov_b32_e32 v26, v0
	v_mov_b32_e32 v27, v0
	v_mov_b32_e32 v28, v0
	v_mov_b32_e32 v29, v0
	v_mov_b32_e32 v30, v0
	v_mov_b32_e32 v31, v0
	v_mov_b32_e32 v32, v0
	v_mov_b32_e32 v33, v0
	v_mov_b32_e32 v34, v0
	v_mov_b32_e32 v35, v0
	v_mov_b32_e32 v36, v0
	v_mov_b32_e32 v37, v0
	v_mov_b32_e32 v38, v0
	v_mov_b32_e32 v39, v0
	v_mov_b32_e32 v40, v0
	v_mov_b32_e32 v41, v0
	v_mov_b32_e32 v42, v0
	v_mov_b32_e32 v43, v0
	v_mov_b32_e32 v44, v0
	v_mov_b32_e32 v45, v0
	v_mov_b32_e32 v46, v0
	v_mov_b32_e32 v47, v0
	v_mov_b32_e32 v48, v0
	v_mov_b32_e32 v49, v0
	v_mov_b32_e32 v50, v0
	v_mov_b32_e32 v51, v0
	v_mov_b32_e32 v52, v0
	v_mov_b32_e32 v53, v0
	v_mov_b32_e32 v54, v0
	v_mov_b32_e32 v55, v0
	v_mov_b32_e32 v56, v0
	v_mov_b32_e32 v57, v0
	v_mov_b32_e32 v58, v0
	v_mov_b32_e32 v59, v0
	v_mov_b32_e32 v60, v0
	v_mov_b32_e32 v61, v0
	v_mov_b32_e32 v62, v0
	v_mov_b32_e32 v63, v0
	v_mov_b32_e32 v64, v0
	v_mov_b32_e32 v65, v0
	v_mov_b32_e32 v66, v0
	v_mov_b32_e32 v67, v0
	v_mov_b32_e32 v68, v0
	v_mov_b32_e32 v69, v0
	v_mov_b32_e32 v70, v0
	v_mov_b32_e32 v71, v0
	v_mov_b32_e32 v72, v0
	v_mov_b32_e32 v73, v0
	v_mov_b32_e32 v74, v0
	v_mov_b32_e32 v75, v0
	v_mov_b32_e32 v76, v0
	v_mov_b32_e32 v77, v0
	v_mov_b32_e32 v78, v0
	v_mov_b32_e32 v79, v0
	v_mov_b32_e32 v80, v0
	v_mov_b32_e32 v81, v0
	v_mov_b32_e32 v82, v0
	v_mov_b32_e32 v83, v0
	v_mov_b32_e32 v84, v0
	v_mov_b32_e32 v85, v0
	v_mov_b32_e32 v86, v0
	v_mov_b32_e32 v87, v0
	v_mov_b32_e32 v88, v0
	v_mov_b32_e32 v89, v0
	v_mov_b32_e32 v90, v0
	v_mov_b32_e32 v91, v0
	v_mov_b32_e32 v92, v0
	v_mov_b32_e32 v93, v0
	v_mov_b32_e32 v94, v0
	v_mov_b32_e32 v95, v0
	v_mov_b32_e32 v96, v0
	v_mov_b32_e32 v97, v0
	v_mov_b32_e32 v98, v0
	v_mov_b32_e32 v99, v0
	v_mov_b32_e32 v100, v0
	v_mov_b32_e32 v101, v0
	v_mov_b32_e32 v102, v0
	v_mov_b32_e32 v103, v0
	v_mov_b32_e32 v104, v0
	v_mov_b32_e32 v105, v0
	v_mov_b32_e32 v106, v0
	v_mov_b32_e32 v107, v0
	v_mov_b32_e32 v108, v0
	v_mov_b32_e32 v109, v0
	v_mov_b32_e32 v110, v0
	v_mov_b32_e32 v111, v0
	v_mov_b32_e32 v112, v0
	v_mov_b32_e32 v113, v0
	v_mov_b32_e32 v114, v0
	v_mov_b32_e32 v115, v0
	v_mov_b32_e32 v116, v0
	v_mov_b32_e32 v117, v0
	v_mov_b32_e32 v118, v0
	v_mov_b32_e32 v119, v0
	v_mov_b32_e32 v120, v0
	v_mov_b32_e32 v121, v0
	v_mov_b32_e32 v122, v0
	v_mov_b32_e32 v123, v0
	v_mov_b32_e32 v124, v0
	v_mov_b32_e32 v125, v0
	v_mov_b32_e32 v126, v0
	v_mov_b32_e32 v127, v0
	v_readfirstlane_b32 s98, v151
	s_waitcnt vmcnt(8)
	s_barrier
	s_cmp_lt_u32 s98, 0x2000
	s_cbranch_scc1 .Lg3_top
	s_barrier
	s_setprio 1

; __device__ __forceinline__ int trow(int j) { const int t = otid(); return ((t >> 6) * 2 + j) * 16 + ((t & 63) >> 2); }
; __device__ __forceinline__ int tkc() { const int l = otid() & 63; return ((l & 3) ^ ((0 - (l >> 4)) & 3)) * 8; }
; template <class MK, class SW, class EPI>
; __device__ __forceinline__ void gemm_phase(int first, int step, int n, int nk, MK mk, SW swapf, EPI epi, char* lds) {
;     ...
;   for (int it = first; it < n; it += step) {
;     const bool has_next = (it + step < n);
;     const TP nxt = mk(has_next ? it + step : it);
;     f32x4 acc[8][4];
;     zero_acc(acc);
;     if (swapf(it)) gemm_main<true>(acc, cur, nk, lds); else gemm_main<false>(acc, cur, nk, lds);
; __device__ __forceinline__ TP moe1_ptrs(const Params& p, int e, int mt, int nt) {
;   const u16* X = (const u16*)(p.ws + OFF_ACT1);
;   const int* idx = (const int*)(p.ws + OFF_IDX);
;   TP t;
;   {
;     const int r0 = mt * 256 + trow(0), r1 = mt * 256 + trow(1);
;     t.a0 = X + (size_t)((r0 >> 8) * 2048 + idx[e * 8192 + r0]) * 1024 + tkc();
;     t.a1 = X + (size_t)((r1 >> 8) * 2048 + idx[e * 8192 + r1]) * 1024 + tkc();
;   }
.LBB0_1299:
	s_mov_b32 s27, s26
	s_add_i32 s26, s26, s3
	s_cmpk_gt_i32 s26, 0x15ff
	s_cselect_b64 s[16:17], -1, 0
	s_cmpk_lt_i32 s26, 0x1600
	s_cselect_b64 s[18:19], -1, 0
	s_and_b64 s[20:21], s[18:19], exec
	s_cselect_b32 s20, s26, s27
	s_mul_hi_i32 s21, s20, 0x2e8ba2e9
	s_lshr_b32 s22, s21, 31
	s_ashr_i32 s21, s21, 7
	s_add_i32 s28, s21, s22
	s_mul_i32 s21, s28, 0x2c0
	s_sub_i32 s20, s20, s21
	s_bfe_u32 s21, s20, 0x5001a
	s_add_i32 s21, s20, s21
	s_sext_i32_i16 s22, s21
	s_and_b32 s21, s21, 0xffe0
	v_mov_b32_e32 v0, v153
	s_sub_i32 s20, s20, s21
	s_sext_i32_i16 s20, s20
	v_ashrrev_i32_e32 v1, 1, v0
	v_bfe_u32 v0, v0, 2, 4
	s_lshl_b32 s20, s20, 8
	v_and_or_b32 v0, v1, s38, v0
	v_add_u32_e32 v134, s20, v0
	v_mov_b32_e32 v0, v153
	s_add_i32 s28, s28, s52
	v_ashrrev_i32_e32 v1, 1, v0
	v_bfe_u32 v0, v0, 2, 4
	v_and_or_b32 v0, v1, s38, v0
	v_add_u32_e32 v0, s20, v0
	s_lshl_b32 s20, s28, 13
	v_or_b32_e32 v147, 16, v0
	v_add_u32_e32 v0, s20, v134
	v_ashrrev_i32_e32 v1, 31, v0
	v_lshl_add_u64 v[0:1], v[0:1], 2, s[58:59]
	global_load_dword v154, v[0:1], off
	v_add_u32_e32 v0, s20, v147
	v_ashrrev_i32_e32 v1, 31, v0
	v_mov_b32_e32 v144, v153
	v_lshl_add_u64 v[0:1], v[0:1], 2, s[58:59]
	global_load_dword v155, v[0:1], off
	v_mov_b32_e32 v146, v153
	v_mov_b32_e32 v151, v153
	v_mov_b32_e32 v145, v153
	v_mov_b32_e32 v149, v153
	v_mov_b32_e32 v0, v153
	s_lshr_b32 s29, s22, 5
	v_lshlrev_b32_e32 v3, 2, v0
	v_and_b32_e32 v3, 48, v3
	v_sub_u32_e32 v3, 0, v3
	v_and_b32_e32 v156, 15, v0
	v_lshlrev_b32_e32 v1, 5, v0
	v_lshlrev_b32_e32 v2, 4, v0
	v_bitop3_b32 v157, v0, 48, v3 bitop3:0x48
	v_ashrrev_i32_e32 v158, 1, v0
	v_lshlrev_b32_e32 v0, 6, v0
	v_and_b32_e32 v1, 0xfffff800, v1
	v_and_b32_e32 v2, 0x3f0, v2
	v_and_or_b32 v3, v158, s2, v156
	v_and_b32_e32 v159, 0x33c0, v0
	v_mov_b32_e32 v0, 0
	v_lshl_or_b32 v160, v3, 6, v157
	v_or_b32_e32 v161, v159, v157
	v_add3_u32 v162, 0, v1, v2
	v_lshl_add_u64 v[136:137], v[136:137], 0, s[42:43]
	v_lshl_add_u64 v[138:139], v[138:139], 0, s[42:43]
	v_lshl_add_u64 v[140:141], v[140:141], 0, s[42:43]
	v_lshl_add_u64 v[142:143], v[142:143], 0, s[42:43]
	s_mov_b32 s20, 0x18000
	v_mov_b32_e32 v1, v0
	v_mov_b32_e32 v2, v0
	v_mov_b32_e32 v3, v0
	v_mov_b32_e32 v4, v0
	v_mov_b32_e32 v5, v0
	v_mov_b32_e32 v6, v0
	v_mov_b32_e32 v7, v0
	v_mov_b32_e32 v8, v0
	v_mov_b32_e32 v9, v0
	v_mov_b32_e32 v10, v0
	v_mov_b32_e32 v11, v0
	v_mov_b32_e32 v12, v0
	v_mov_b32_e32 v13, v0
	v_mov_b32_e32 v14, v0
	v_mov_b32_e32 v15, v0
	v_mov_b32_e32 v16, v0
	v_mov_b32_e32 v17, v0
	v_mov_b32_e32 v18, v0
	v_mov_b32_e32 v19, v0
	v_mov_b32_e32 v20, v0
	v_mov_b32_e32 v21, v0
	v_mov_b32_e32 v22, v0
	v_mov_b32_e32 v23, v0
	v_mov_b32_e32 v24, v0
	v_mov_b32_e32 v25, v0
	v_mov_b32_e32 v26, v0
	v_mov_b32_e32 v27, v0
	v_mov_b32_e32 v28, v0
	v_mov_b32_e32 v29, v0
	v_mov_b32_e32 v30, v0
	v_mov_b32_e32 v31, v0
	v_mov_b32_e32 v32, v0
	v_mov_b32_e32 v33, v0
	v_mov_b32_e32 v34, v0
	v_mov_b32_e32 v35, v0
	v_mov_b32_e32 v36, v0
	v_mov_b32_e32 v37, v0
	v_mov_b32_e32 v38, v0
	v_mov_b32_e32 v39, v0
	v_mov_b32_e32 v40, v0
	v_mov_b32_e32 v41, v0
	v_mov_b32_e32 v42, v0
	v_mov_b32_e32 v43, v0
	v_mov_b32_e32 v44, v0
	v_mov_b32_e32 v45, v0
	v_mov_b32_e32 v46, v0
	v_mov_b32_e32 v47, v0
	v_mov_b32_e32 v48, v0
	v_mov_b32_e32 v49, v0
	v_mov_b32_e32 v50, v0
	v_mov_b32_e32 v51, v0
	v_mov_b32_e32 v52, v0
	v_mov_b32_e32 v53, v0
	v_mov_b32_e32 v54, v0
	v_mov_b32_e32 v55, v0
	v_mov_b32_e32 v56, v0
	v_mov_b32_e32 v57, v0
	v_mov_b32_e32 v58, v0
	v_mov_b32_e32 v59, v0
	v_mov_b32_e32 v60, v0
	v_mov_b32_e32 v61, v0
	v_mov_b32_e32 v62, v0
	v_mov_b32_e32 v63, v0
	v_mov_b32_e32 v64, v0
	v_mov_b32_e32 v65, v0
	v_mov_b32_e32 v66, v0
	v_mov_b32_e32 v67, v0
	v_mov_b32_e32 v68, v0
	v_mov_b32_e32 v69, v0
	v_mov_b32_e32 v70, v0
	v_mov_b32_e32 v71, v0
	v_mov_b32_e32 v72, v0
	v_mov_b32_e32 v73, v0
	v_mov_b32_e32 v74, v0
	v_mov_b32_e32 v75, v0
	v_mov_b32_e32 v76, v0
	v_mov_b32_e32 v77, v0
	v_mov_b32_e32 v78, v0
	v_mov_b32_e32 v79, v0
	v_mov_b32_e32 v80, v0
	v_mov_b32_e32 v81, v0
	v_mov_b32_e32 v82, v0
	v_mov_b32_e32 v83, v0
	v_mov_b32_e32 v84, v0
	v_mov_b32_e32 v85, v0
	v_mov_b32_e32 v86, v0
	v_mov_b32_e32 v87, v0
	v_mov_b32_e32 v88, v0
	v_mov_b32_e32 v89, v0
	v_mov_b32_e32 v90, v0
	v_mov_b32_e32 v91, v0
	v_mov_b32_e32 v92, v0
	v_mov_b32_e32 v93, v0
	v_mov_b32_e32 v94, v0
	v_mov_b32_e32 v95, v0
	v_mov_b32_e32 v96, v0
	v_mov_b32_e32 v97, v0
	v_mov_b32_e32 v98, v0
	v_mov_b32_e32 v99, v0
	v_mov_b32_e32 v100, v0
	v_mov_b32_e32 v101, v0
	v_mov_b32_e32 v102, v0
	v_mov_b32_e32 v103, v0
	v_mov_b32_e32 v104, v0
	v_mov_b32_e32 v105, v0
	v_mov_b32_e32 v106, v0
	v_mov_b32_e32 v107, v0
	v_mov_b32_e32 v108, v0
	v_mov_b32_e32 v109, v0
	v_mov_b32_e32 v110, v0
	v_mov_b32_e32 v111, v0
	v_mov_b32_e32 v112, v0
	v_mov_b32_e32 v113, v0
	v_mov_b32_e32 v114, v0
	v_mov_b32_e32 v115, v0
	v_mov_b32_e32 v116, v0
	v_mov_b32_e32 v117, v0
	v_mov_b32_e32 v118, v0
	v_mov_b32_e32 v119, v0
	v_mov_b32_e32 v120, v0
	v_mov_b32_e32 v121, v0
	v_mov_b32_e32 v122, v0
	v_mov_b32_e32 v123, v0
	v_mov_b32_e32 v124, v0
	v_mov_b32_e32 v125, v0
	v_mov_b32_e32 v126, v0
	v_mov_b32_e32 v127, v0
	v_readfirstlane_b32 s98, v162
	s_waitcnt vmcnt(8)
	s_barrier
	s_cmp_lt_u32 s98, 0x2000
	s_cbranch_scc1 .Lmoe1_top
	s_barrier
	s_setprio 1

; __device__ __forceinline__ int trow(int j) { const int t = otid(); return ((t >> 6) * 2 + j) * 16 + ((t & 63) >> 2); }
; __device__ __forceinline__ int tkc() { const int l = otid() & 63; return ((l & 3) ^ ((0 - (l >> 4)) & 3)) * 8; }
; __device__ __forceinline__ int perm_row(int R) { return (R & ~63) | (((R >> 2) & 3) * 16 + ((R >> 4) & 3) * 4 + (R & 3)); }
; __device__ __forceinline__ TP moe2_ptrs(const Params& p, int e, int el, int mt, int nt) {
;   TP t;
;   t.a0 = (const u16*)(p.ws + OFF_H) + (size_t)el * 8192 * 2816 + (size_t)(mt * 256 + trow(0)) * 2816 + tkc(); t.a1 = t.a0 + 16 * 2816;
;   t.b0 = (const u16*)(p.ws + OFF_WD) + (size_t)e * 1024 * 2816 + (size_t)(nt * 256 + perm_row(trow(0))) * 2816 + tkc();
;   t.b1 = (const u16*)(p.ws + OFF_WD) + (size_t)e * 1024 * 2816 + (size_t)(nt * 256 + perm_row(trow(1))) * 2816 + tkc();
;   return t;
; }
; __global__ void __launch_bounds__(NTHR) fwd_megakernel(Params p) {
;     ...
;     gemm_phase(bid, G, 8 * 32 * 4, 88,
;       [&](int it) { const int el = it >> 7, rem = it & 127; return moe2_ptrs(p, grp * 8 + el, el, rem & 31, rem >> 5); },
;       [&](int it) { return true; },
;       [&](int it, f32x4 (&acc)[8][4]) { const int el = it >> 7, rem = it & 127; moe2_epi(p, grp * 8 + el, el, rem & 31, rem >> 5, acc); }, lds);
.LBB0_1368:
	v_mov_b32_e32 v146, v153
	v_mov_b32_e32 v134, v153
	v_mov_b32_e32 v145, v153
	v_mov_b32_e32 v142, v153
	v_mov_b32_e32 v144, v153
	v_mov_b32_e32 v143, v153
	v_mov_b32_e32 v0, v153
	s_mov_b64 s[14:15], 0x160c0
	v_lshlrev_b32_e32 v3, 2, v0
	v_and_b32_e32 v3, 48, v3
	v_sub_u32_e32 v3, 0, v3
	v_and_b32_e32 v147, 15, v0
	v_lshlrev_b32_e32 v1, 5, v0
	v_lshlrev_b32_e32 v2, 4, v0
	v_bitop3_b32 v149, v0, 48, v3 bitop3:0x48
	v_ashrrev_i32_e32 v151, 1, v0
	v_lshlrev_b32_e32 v0, 6, v0
	v_and_b32_e32 v1, 0xfffff800, v1
	v_and_b32_e32 v2, 0x3f0, v2
	v_and_or_b32 v3, v151, s2, v147
	v_and_b32_e32 v154, 0x33c0, v0
	v_mov_b32_e32 v0, 0
	s_mov_b32 s22, s18
	v_lshl_or_b32 v155, v3, 6, v149
	v_or_b32_e32 v156, v154, v149
	v_add3_u32 v157, 0, v1, v2
	v_lshl_add_u64 v[136:137], v[136:137], 0, s[14:15]
	v_lshl_add_u64 v[138:139], v[138:139], 0, s[42:43]
	v_lshl_add_u64 v[140:141], v[140:141], 0, s[42:43]
	s_mov_b32 s14, 0x18000
	v_mov_b32_e32 v1, v0
	v_mov_b32_e32 v2, v0
	v_mov_b32_e32 v3, v0
	v_mov_b32_e32 v4, v0
	v_mov_b32_e32 v5, v0
	v_mov_b32_e32 v6, v0
	v_mov_b32_e32 v7, v0
	v_mov_b32_e32 v8, v0
	v_mov_b32_e32 v9, v0
	v_mov_b32_e32 v10, v0
	v_mov_b32_e32 v11, v0
	v_mov_b32_e32 v12, v0
	v_mov_b32_e32 v13, v0
	v_mov_b32_e32 v14, v0
	v_mov_b32_e32 v15, v0
	v_mov_b32_e32 v16, v0
	v_mov_b32_e32 v17, v0
	v_mov_b32_e32 v18, v0
	v_mov_b32_e32 v19, v0
	v_mov_b32_e32 v20, v0
	v_mov_b32_e32 v21, v0
	v_mov_b32_e32 v22, v0
	v_mov_b32_e32 v23, v0
	v_mov_b32_e32 v24, v0
	v_mov_b32_e32 v25, v0
	v_mov_b32_e32 v26, v0
	v_mov_b32_e32 v27, v0
	v_mov_b32_e32 v28, v0
	v_mov_b32_e32 v29, v0
	v_mov_b32_e32 v30, v0
	v_mov_b32_e32 v31, v0
	v_mov_b32_e32 v32, v0
	v_mov_b32_e32 v33, v0
	v_mov_b32_e32 v34, v0
	v_mov_b32_e32 v35, v0
	v_mov_b32_e32 v36, v0
	v_mov_b32_e32 v37, v0
	v_mov_b32_e32 v38, v0
	v_mov_b32_e32 v39, v0
	v_mov_b32_e32 v40, v0
	v_mov_b32_e32 v41, v0
	v_mov_b32_e32 v42, v0
	v_mov_b32_e32 v43, v0
	v_mov_b32_e32 v44, v0
	v_mov_b32_e32 v45, v0
	v_mov_b32_e32 v46, v0
	v_mov_b32_e32 v47, v0
	v_mov_b32_e32 v48, v0
	v_mov_b32_e32 v49, v0
	v_mov_b32_e32 v50, v0
	v_mov_b32_e32 v51, v0
	v_mov_b32_e32 v52, v0
	v_mov_b32_e32 v53, v0
	v_mov_b32_e32 v54, v0
	v_mov_b32_e32 v55, v0
	v_mov_b32_e32 v56, v0
	v_mov_b32_e32 v57, v0
	v_mov_b32_e32 v58, v0
	v_mov_b32_e32 v59, v0
	v_mov_b32_e32 v60, v0
	v_mov_b32_e32 v61, v0
	v_mov_b32_e32 v62, v0
	v_mov_b32_e32 v63, v0
	v_mov_b32_e32 v64, v0
	v_mov_b32_e32 v65, v0
	v_mov_b32_e32 v66, v0
	v_mov_b32_e32 v67, v0
	v_mov_b32_e32 v68, v0
	v_mov_b32_e32 v69, v0
	v_mov_b32_e32 v70, v0
	v_mov_b32_e32 v71, v0
	v_mov_b32_e32 v72, v0
	v_mov_b32_e32 v73, v0
	v_mov_b32_e32 v74, v0
	v_mov_b32_e32 v75, v0
	v_mov_b32_e32 v76, v0
	v_mov_b32_e32 v77, v0
	v_mov_b32_e32 v78, v0
	v_mov_b32_e32 v79, v0
	v_mov_b32_e32 v80, v0
	v_mov_b32_e32 v81, v0
	v_mov_b32_e32 v82, v0
	v_mov_b32_e32 v83, v0
	v_mov_b32_e32 v84, v0
	v_mov_b32_e32 v85, v0
	v_mov_b32_e32 v86, v0
	v_mov_b32_e32 v87, v0
	v_mov_b32_e32 v88, v0
	v_mov_b32_e32 v89, v0
	v_mov_b32_e32 v90, v0
	v_mov_b32_e32 v91, v0
	v_mov_b32_e32 v92, v0
	v_mov_b32_e32 v93, v0
	v_mov_b32_e32 v94, v0
	v_mov_b32_e32 v95, v0
	v_mov_b32_e32 v96, v0
	v_mov_b32_e32 v97, v0
	v_mov_b32_e32 v98, v0
	v_mov_b32_e32 v99, v0
	v_mov_b32_e32 v100, v0
	v_mov_b32_e32 v101, v0
	v_mov_b32_e32 v102, v0
	v_mov_b32_e32 v103, v0
	v_mov_b32_e32 v104, v0
	v_mov_b32_e32 v105, v0
	v_mov_b32_e32 v106, v0
	v_mov_b32_e32 v107, v0
	v_mov_b32_e32 v108, v0
	v_mov_b32_e32 v109, v0
	v_mov_b32_e32 v110, v0
	v_mov_b32_e32 v111, v0
	v_mov_b32_e32 v112, v0
	v_mov_b32_e32 v113, v0
	v_mov_b32_e32 v114, v0
	v_mov_b32_e32 v115, v0
	v_mov_b32_e32 v116, v0
	v_mov_b32_e32 v117, v0
	v_mov_b32_e32 v118, v0
	v_mov_b32_e32 v119, v0
	v_mov_b32_e32 v120, v0
	v_mov_b32_e32 v121, v0
	v_mov_b32_e32 v122, v0
	v_mov_b32_e32 v123, v0
	v_mov_b32_e32 v124, v0
	v_mov_b32_e32 v125, v0
	v_mov_b32_e32 v126, v0
	v_mov_b32_e32 v127, v0
	s_mov_b32 s18, 0xfffea000
	s_mov_b32 s19, -1
	v_readfirstlane_b32 s98, v157
	s_waitcnt vmcnt(8)
	s_barrier
	s_cmp_lt_u32 s98, 0x2000
	s_cbranch_scc1 .Lmoe2_top
	s_barrier
	s_setprio 1
